# C1 pooling phase rewritten: 4-row x 4-group items (skips always-masked window taps), saddr 32-bit offsets, per-group software-pipelined loads with counted vmcnt; on top of GLA changes
# speedup vs baseline: 1.0063x; 1.0063x over previous
; __device__ __forceinline__ float bflo(unsigned u) { return __uint_as_float(u << 16); }
; __device__ __forceinline__ float bfhi(unsigned u) { return __uint_as_float(u & 0xffff0000u); }
; template <int l> __device__ __forceinline__ void layer_body(LAS unsigned char* lds, const int wave_s) {
;     ...
;         for (int row = gw; row < rows_post; row += NGW) {
;             int pos, Ls; if (row < TL) { pos = row & 63; Ls = 64; } else { pos = (row - TL) & 255; Ls = 256; }
;             const int hw = 1 << (lane >> 4);
;             const int lo = max(pos - hw, 0), hi = min(pos + hw, Ls);
;             const bf16* base = POOLb + (size_t)(row - pos) * 512 + 8 * lane;
;             float s[8];
; #pragma unroll
;             for (int e = 0; e < 8; ++e) s[e] = 0.f;
;             v4u av[16];
; #pragma unroll
;             for (int k = 0; k < 16; ++k) { const int p = lo + k; const int pc = p < hi ? p : pos; av[k] = *(const v4u*)(base + (size_t)pc * 512); }
; #pragma unroll
;             for (int k = 0; k < 16; ++k) { const float vm = (lo + k < hi) ? 1.f : 0.f; const v4u a = av[k];
;                 s[0] += vm * bflo(a.x); s[1] += vm * bfhi(a.x); s[2] += vm * bflo(a.y); s[3] += vm * bfhi(a.y); s[4] += vm * bflo(a.z); s[5] += vm * bfhi(a.z); s[6] += vm * bflo(a.w); s[7] += vm * bfhi(a.w); }
;             const v4u me = *(const v4u*)(base + (size_t)pos * 512); const float inv = 1.0f / (float)(hi - lo);
.LBB0_419:
	s_cmp_lt_i32 s80, 0x11000
	s_cselect_b64 s[2:3], -1, 0
	v_writelane_b32 v255, s2, 4
	s_mov_b64 s[0:1], s[84:85]
	s_cmp_gt_i32 s80, 0x10fff
	v_writelane_b32 v255, s3, 5
	s_waitcnt lgkmcnt(0)
	s_barrier
	v_mbcnt_lo_u32_b32 v0, -1, 0
	v_mbcnt_hi_u32_b32 v0, -1, v0
	s_cbranch_scc1 .LBB0_422
	s_load_dwordx2 s[2:3], s[84:85], 0xd0
	v_lshrrev_b32_e32 v170, 4, v0
	v_and_b32_e32 v171, 15, v0
	v_lshlrev_b32_e32 v171, 4, v171
	v_lshl_add_u32 v174, v170, 10, v171
	s_mov_b32 s4, s80
	s_waitcnt lgkmcnt(0)
	s_add_u32 s22, s2, 0x11f00000
	s_addc_u32 s23, s3, 0
	s_add_u32 s24, s2, 0x1eb00000
	s_addc_u32 s25, s3, 0
	s_lshl_b32 s6, s4, 2
	s_cmp_lt_i32 s6, 0x10000
	s_cselect_b32 s26, 63, 0xff
	s_cselect_b32 s19, 64, 0x100
	s_and_b32 s18, s6, s26
	s_sub_i32 s27, s6, s18
	s_lshl_b32 s27, s27, 10
	v_add_u32_e32 v172, s18, v170
	v_add_u32_e32 v173, s27, v171
	v_subrev_u32_e32 v176, 1, v172
	v_add_u32_e32 v177, 1, v172
	v_max_i32_e32 v176, 0, v176
	v_min_i32_e32 v177, s19, v177
	v_lshl_add_u32 v187, v172, 10, v173
	v_sub_u32_e32 v178, v177, v176
	global_load_dwordx4 v[0:3], v187, s[22:23]
	v_lshl_add_u32 v188, v176, 10, v173
	v_mov_b32_e32 v136, 1.0
	global_load_dwordx4 v[4:7], v188, s[22:23]
	v_add_u32_e32 v179, 1, v176
	v_cmp_lt_i32_e64 s[30:31], v179, v177
	s_nop 1
	v_cndmask_b32_e64 v183, v172, v179, s[30:31]
	v_cndmask_b32_e64 v137, 0, 1.0, s[30:31]
	v_lshl_add_u32 v187, v183, 10, v173
	global_load_dwordx4 v[8:11], v187, s[22:23]
	v_cvt_f32_i32_e32 v178, v178
	v_div_scale_f32 v212, s[40:41], v178, v178, 1.0
	v_div_scale_f32 v215, vcc, 1.0, v178, 1.0
	v_rcp_f32_e32 v213, v212
	s_nop 0
	v_fma_f32 v214, -v212, v213, 1.0
	v_fmac_f32_e32 v213, v214, v213
	v_mul_f32_e32 v216, v215, v213
	v_fma_f32 v217, -v212, v216, v215
	v_fmac_f32_e32 v216, v217, v213
	v_fma_f32 v218, -v212, v216, v215
	v_div_fmas_f32 v219, v218, v213, v216
	v_div_fixup_f32 v166, v219, v178, 1.0
	v_subrev_u32_e32 v176, 2, v172
	v_add_u32_e32 v177, 2, v172
	v_max_i32_e32 v176, 0, v176
	v_min_i32_e32 v177, s19, v177
	v_lshl_add_u32 v187, v172, 10, v173
	v_sub_u32_e32 v178, v177, v176
	global_load_dwordx4 v[12:15], v187, s[22:23] offset:256
	v_lshl_add_u32 v188, v176, 10, v173
	v_mov_b32_e32 v138, 1.0
	global_load_dwordx4 v[16:19], v188, s[22:23] offset:256
	v_add_u32_e32 v179, 1, v176
	v_add_u32_e32 v180, 2, v176
	v_add_u32_e32 v181, 3, v176
	v_cmp_lt_i32_e64 s[30:31], v179, v177
	v_cmp_lt_i32_e64 s[34:35], v180, v177
	v_cmp_lt_i32_e64 s[36:37], v181, v177
	v_cndmask_b32_e64 v183, v172, v179, s[30:31]
	v_cndmask_b32_e64 v139, 0, 1.0, s[30:31]
	v_lshl_add_u32 v187, v183, 10, v173
	global_load_dwordx4 v[20:23], v187, s[22:23] offset:256
	v_cndmask_b32_e64 v184, v172, v180, s[34:35]
	v_cndmask_b32_e64 v140, 0, 1.0, s[34:35]
	v_lshl_add_u32 v188, v184, 10, v173
	global_load_dwordx4 v[24:27], v188, s[22:23] offset:256
	v_cndmask_b32_e64 v185, v172, v181, s[36:37]
	v_cndmask_b32_e64 v141, 0, 1.0, s[36:37]
	v_lshl_add_u32 v189, v185, 10, v173
	global_load_dwordx4 v[28:31], v189, s[22:23] offset:256
	v_cvt_f32_i32_e32 v178, v178
	v_div_scale_f32 v212, s[40:41], v178, v178, 1.0
	v_div_scale_f32 v215, vcc, 1.0, v178, 1.0
	v_rcp_f32_e32 v213, v212
	s_nop 0
	v_fma_f32 v214, -v212, v213, 1.0
	v_fmac_f32_e32 v213, v214, v213
	v_mul_f32_e32 v216, v215, v213
	v_fma_f32 v217, -v212, v216, v215
	v_fmac_f32_e32 v216, v217, v213
	v_fma_f32 v218, -v212, v216, v215
	v_div_fmas_f32 v219, v218, v213, v216
	v_div_fixup_f32 v167, v219, v178, 1.0
	v_subrev_u32_e32 v176, 4, v172
	v_add_u32_e32 v177, 4, v172
	v_max_i32_e32 v176, 0, v176
	v_min_i32_e32 v177, s19, v177
	v_lshl_add_u32 v187, v172, 10, v173
	v_sub_u32_e32 v178, v177, v176
	global_load_dwordx4 v[32:35], v187, s[22:23] offset:512
	v_lshl_add_u32 v188, v176, 10, v173
	v_mov_b32_e32 v142, 1.0
	global_load_dwordx4 v[36:39], v188, s[22:23] offset:512
	v_add_u32_e32 v179, 1, v176
	v_add_u32_e32 v180, 2, v176
	v_add_u32_e32 v181, 3, v176
	v_add_u32_e32 v182, 4, v176
	v_cmp_lt_i32_e64 s[30:31], v179, v177
	v_cmp_lt_i32_e64 s[34:35], v180, v177
	v_cmp_lt_i32_e64 s[36:37], v181, v177
	v_cmp_lt_i32_e64 s[38:39], v182, v177
	v_cndmask_b32_e64 v183, v172, v179, s[30:31]
	v_cndmask_b32_e64 v143, 0, 1.0, s[30:31]
	v_lshl_add_u32 v187, v183, 10, v173
	global_load_dwordx4 v[40:43], v187, s[22:23] offset:512
	v_cndmask_b32_e64 v184, v172, v180, s[34:35]
	v_cndmask_b32_e64 v144, 0, 1.0, s[34:35]
	v_lshl_add_u32 v188, v184, 10, v173
	global_load_dwordx4 v[44:47], v188, s[22:23] offset:512
	v_cndmask_b32_e64 v185, v172, v181, s[36:37]
	v_cndmask_b32_e64 v145, 0, 1.0, s[36:37]
	v_lshl_add_u32 v189, v185, 10, v173
	global_load_dwordx4 v[48:51], v189, s[22:23] offset:512
	v_cndmask_b32_e64 v186, v172, v182, s[38:39]
	v_cndmask_b32_e64 v146, 0, 1.0, s[38:39]
	v_lshl_add_u32 v190, v186, 10, v173
	global_load_dwordx4 v[52:55], v190, s[22:23] offset:512
	v_add_u32_e32 v179, 5, v176
	v_add_u32_e32 v180, 6, v176
	v_add_u32_e32 v181, 7, v176
	v_cmp_lt_i32_e64 s[30:31], v179, v177
	v_cmp_lt_i32_e64 s[34:35], v180, v177
	v_cmp_lt_i32_e64 s[36:37], v181, v177
	v_cndmask_b32_e64 v183, v172, v179, s[30:31]
	v_cndmask_b32_e64 v147, 0, 1.0, s[30:31]
	v_lshl_add_u32 v187, v183, 10, v173
	global_load_dwordx4 v[56:59], v187, s[22:23] offset:512
	v_cndmask_b32_e64 v184, v172, v180, s[34:35]
	v_cndmask_b32_e64 v148, 0, 1.0, s[34:35]
	v_lshl_add_u32 v188, v184, 10, v173
	global_load_dwordx4 v[60:63], v188, s[22:23] offset:512
	v_cndmask_b32_e64 v185, v172, v181, s[36:37]
	v_cndmask_b32_e64 v149, 0, 1.0, s[36:37]
	v_lshl_add_u32 v189, v185, 10, v173
	global_load_dwordx4 v[64:67], v189, s[22:23] offset:512
	v_cvt_f32_i32_e32 v178, v178
	v_div_scale_f32 v212, s[40:41], v178, v178, 1.0
; __device__ __forceinline__ float bflo(unsigned u) { return __uint_as_float(u << 16); }
; __device__ __forceinline__ float bfhi(unsigned u) { return __uint_as_float(u & 0xffff0000u); }
; template <int l> __device__ __forceinline__ void layer_body(LAS unsigned char* lds, const int wave_s) {
;     ...
;         for (int row = gw; row < rows_post; row += NGW) {
;             int pos, Ls; if (row < TL) { pos = row & 63; Ls = 64; } else { pos = (row - TL) & 255; Ls = 256; }
;             const int hw = 1 << (lane >> 4);
;             const int lo = max(pos - hw, 0), hi = min(pos + hw, Ls);
;             const bf16* base = POOLb + (size_t)(row - pos) * 512 + 8 * lane;
;             float s[8];
; #pragma unroll
;             for (int e = 0; e < 8; ++e) s[e] = 0.f;
;             v4u av[16];
; #pragma unroll
;             for (int k = 0; k < 16; ++k) { const int p = lo + k; const int pc = p < hi ? p : pos; av[k] = *(const v4u*)(base + (size_t)pc * 512); }
; #pragma unroll
;             for (int k = 0; k < 16; ++k) { const float vm = (lo + k < hi) ? 1.f : 0.f; const v4u a = av[k];
;                 s[0] += vm * bflo(a.x); s[1] += vm * bfhi(a.x); s[2] += vm * bflo(a.y); s[3] += vm * bfhi(a.y); s[4] += vm * bflo(a.z); s[5] += vm * bfhi(a.z); s[6] += vm * bflo(a.w); s[7] += vm * bfhi(a.w); }
;             const v4u me = *(const v4u*)(base + (size_t)pos * 512); const float inv = 1.0f / (float)(hi - lo);
	v_div_scale_f32 v215, vcc, 1.0, v178, 1.0
	v_rcp_f32_e32 v213, v212
	s_nop 0
	v_fma_f32 v214, -v212, v213, 1.0
	v_fmac_f32_e32 v213, v214, v213
	v_mul_f32_e32 v216, v215, v213
	v_fma_f32 v217, -v212, v216, v215
	v_fmac_f32_e32 v216, v217, v213
	v_fma_f32 v218, -v212, v216, v215
	v_div_fmas_f32 v219, v218, v213, v216
	v_div_fixup_f32 v168, v219, v178, 1.0
	v_subrev_u32_e32 v176, 8, v172
	v_add_u32_e32 v177, 8, v172
	v_max_i32_e32 v176, 0, v176
	v_min_i32_e32 v177, s19, v177
	v_lshl_add_u32 v187, v172, 10, v173
	v_sub_u32_e32 v178, v177, v176
	global_load_dwordx4 v[68:71], v187, s[22:23] offset:768
	v_lshl_add_u32 v188, v176, 10, v173
	v_mov_b32_e32 v150, 1.0
	global_load_dwordx4 v[72:75], v188, s[22:23] offset:768
	v_add_u32_e32 v179, 1, v176
	v_add_u32_e32 v180, 2, v176
	v_add_u32_e32 v181, 3, v176
	v_add_u32_e32 v182, 4, v176
	v_cmp_lt_i32_e64 s[30:31], v179, v177
	v_cmp_lt_i32_e64 s[34:35], v180, v177
	v_cmp_lt_i32_e64 s[36:37], v181, v177
	v_cmp_lt_i32_e64 s[38:39], v182, v177
	v_cndmask_b32_e64 v183, v172, v179, s[30:31]
	v_cndmask_b32_e64 v151, 0, 1.0, s[30:31]
	v_lshl_add_u32 v187, v183, 10, v173
	global_load_dwordx4 v[76:79], v187, s[22:23] offset:768
	v_cndmask_b32_e64 v184, v172, v180, s[34:35]
	v_cndmask_b32_e64 v152, 0, 1.0, s[34:35]
	v_lshl_add_u32 v188, v184, 10, v173
	global_load_dwordx4 v[80:83], v188, s[22:23] offset:768
	v_cndmask_b32_e64 v185, v172, v181, s[36:37]
	v_cndmask_b32_e64 v153, 0, 1.0, s[36:37]
	v_lshl_add_u32 v189, v185, 10, v173
	global_load_dwordx4 v[84:87], v189, s[22:23] offset:768
	v_cndmask_b32_e64 v186, v172, v182, s[38:39]
	v_cndmask_b32_e64 v154, 0, 1.0, s[38:39]
	v_lshl_add_u32 v190, v186, 10, v173
	global_load_dwordx4 v[88:91], v190, s[22:23] offset:768
	v_add_u32_e32 v179, 5, v176
	v_add_u32_e32 v180, 6, v176
	v_add_u32_e32 v181, 7, v176
	v_add_u32_e32 v182, 8, v176
	v_cmp_lt_i32_e64 s[30:31], v179, v177
	v_cmp_lt_i32_e64 s[34:35], v180, v177
	v_cmp_lt_i32_e64 s[36:37], v181, v177
	v_cmp_lt_i32_e64 s[38:39], v182, v177
	v_cndmask_b32_e64 v183, v172, v179, s[30:31]
	v_cndmask_b32_e64 v155, 0, 1.0, s[30:31]
	v_lshl_add_u32 v187, v183, 10, v173
	global_load_dwordx4 v[92:95], v187, s[22:23] offset:768
	v_cndmask_b32_e64 v184, v172, v180, s[34:35]
	v_cndmask_b32_e64 v156, 0, 1.0, s[34:35]
	v_lshl_add_u32 v188, v184, 10, v173
	global_load_dwordx4 v[96:99], v188, s[22:23] offset:768
	v_cndmask_b32_e64 v185, v172, v181, s[36:37]
	v_cndmask_b32_e64 v157, 0, 1.0, s[36:37]
	v_lshl_add_u32 v189, v185, 10, v173
	global_load_dwordx4 v[100:103], v189, s[22:23] offset:768
	v_cndmask_b32_e64 v186, v172, v182, s[38:39]
	v_cndmask_b32_e64 v158, 0, 1.0, s[38:39]
	v_lshl_add_u32 v190, v186, 10, v173
	global_load_dwordx4 v[104:107], v190, s[22:23] offset:768
	v_add_u32_e32 v179, 9, v176
	v_add_u32_e32 v180, 10, v176
	v_add_u32_e32 v181, 11, v176
	v_add_u32_e32 v182, 12, v176
	v_cmp_lt_i32_e64 s[30:31], v179, v177
	v_cmp_lt_i32_e64 s[34:35], v180, v177
	v_cmp_lt_i32_e64 s[36:37], v181, v177
	v_cmp_lt_i32_e64 s[38:39], v182, v177
	v_cndmask_b32_e64 v183, v172, v179, s[30:31]
	v_cndmask_b32_e64 v159, 0, 1.0, s[30:31]
	v_lshl_add_u32 v187, v183, 10, v173
	global_load_dwordx4 v[108:111], v187, s[22:23] offset:768
	v_cndmask_b32_e64 v184, v172, v180, s[34:35]
	v_cndmask_b32_e64 v160, 0, 1.0, s[34:35]
	v_lshl_add_u32 v188, v184, 10, v173
	global_load_dwordx4 v[112:115], v188, s[22:23] offset:768
	v_cndmask_b32_e64 v185, v172, v181, s[36:37]
	v_cndmask_b32_e64 v161, 0, 1.0, s[36:37]
	v_lshl_add_u32 v189, v185, 10, v173
	global_load_dwordx4 v[116:119], v189, s[22:23] offset:768
	v_cndmask_b32_e64 v186, v172, v182, s[38:39]
	v_cndmask_b32_e64 v162, 0, 1.0, s[38:39]
	v_lshl_add_u32 v190, v186, 10, v173
	global_load_dwordx4 v[120:123], v190, s[22:23] offset:768
	v_add_u32_e32 v179, 13, v176
	v_add_u32_e32 v180, 14, v176
	v_add_u32_e32 v181, 15, v176
	v_cmp_lt_i32_e64 s[30:31], v179, v177
	v_cmp_lt_i32_e64 s[34:35], v180, v177
	v_cmp_lt_i32_e64 s[36:37], v181, v177
	v_cndmask_b32_e64 v183, v172, v179, s[30:31]
	v_cndmask_b32_e64 v163, 0, 1.0, s[30:31]
	v_lshl_add_u32 v187, v183, 10, v173
	global_load_dwordx4 v[124:127], v187, s[22:23] offset:768
	v_cndmask_b32_e64 v184, v172, v180, s[34:35]
	v_cndmask_b32_e64 v164, 0, 1.0, s[34:35]
	v_lshl_add_u32 v188, v184, 10, v173
	global_load_dwordx4 v[128:131], v188, s[22:23] offset:768
	v_cndmask_b32_e64 v185, v172, v181, s[36:37]
	v_cndmask_b32_e64 v165, 0, 1.0, s[36:37]
	v_lshl_add_u32 v189, v185, 10, v173
	global_load_dwordx4 v[132:135], v189, s[22:23] offset:768
	v_cvt_f32_i32_e32 v178, v178
	v_div_scale_f32 v212, s[40:41], v178, v178, 1.0
	v_div_scale_f32 v215, vcc, 1.0, v178, 1.0
	v_rcp_f32_e32 v213, v212
	s_nop 0
	v_fma_f32 v214, -v212, v213, 1.0
	v_fmac_f32_e32 v213, v214, v213
	v_mul_f32_e32 v216, v215, v213
	v_fma_f32 v217, -v212, v216, v215
	v_fmac_f32_e32 v216, v217, v213
	v_fma_f32 v218, -v212, v216, v215
	v_div_fmas_f32 v219, v218, v213, v216
	v_div_fixup_f32 v169, v219, v178, 1.0
; __device__ __forceinline__ unsigned cvtpk(float lo, float hi) { f32x2 v = {lo, hi}; bf16x2_t b = __builtin_convertvector(v, bf16x2_t); return __builtin_bit_cast(unsigned, b); }
; __device__ __forceinline__ float bflo(unsigned u) { return __uint_as_float(u << 16); }
; __device__ __forceinline__ float bfhi(unsigned u) { return __uint_as_float(u & 0xffff0000u); }
; template <int l> __device__ __forceinline__ void layer_body(LAS unsigned char* lds, const int wave_s) {
;     ...
;         for (int row = gw; row < rows_post; row += NGW) {
;             int pos, Ls; if (row < TL) { pos = row & 63; Ls = 64; } else { pos = (row - TL) & 255; Ls = 256; }
;             const int hw = 1 << (lane >> 4);
;             const int lo = max(pos - hw, 0), hi = min(pos + hw, Ls);
;             const bf16* base = POOLb + (size_t)(row - pos) * 512 + 8 * lane;
;             float s[8];
; #pragma unroll
;             for (int e = 0; e < 8; ++e) s[e] = 0.f;
;             v4u av[16];
; #pragma unroll
;             for (int k = 0; k < 16; ++k) { const int p = lo + k; const int pc = p < hi ? p : pos; av[k] = *(const v4u*)(base + (size_t)pc * 512); }
; #pragma unroll
;             for (int k = 0; k < 16; ++k) { const float vm = (lo + k < hi) ? 1.f : 0.f; const v4u a = av[k];
;                 s[0] += vm * bflo(a.x); s[1] += vm * bfhi(a.x); s[2] += vm * bflo(a.y); s[3] += vm * bfhi(a.y); s[4] += vm * bflo(a.z); s[5] += vm * bfhi(a.z); s[6] += vm * bflo(a.w); s[7] += vm * bfhi(a.w); }
;             const v4u me = *(const v4u*)(base + (size_t)pos * 512); const float inv = 1.0f / (float)(hi - lo);
;             v4u w; w.x = cvtpk(s[0] * inv - bflo(me.x), s[1] * inv - bfhi(me.x)); w.y = cvtpk(s[2] * inv - bflo(me.y), s[3] * inv - bfhi(me.y));
;             w.z = cvtpk(s[4] * inv - bflo(me.z), s[5] * inv - bfhi(me.z)); w.w = cvtpk(s[6] * inv - bflo(me.w), s[7] * inv - bfhi(me.w));
;             *(v4u*)(POOLEDb + (size_t)row * 512 + 8 * lane) = w;
.Lc1_loop_L0:
	s_lshl_b32 s28, s4, 12
	v_add_u32_e32 v175, s28, v174
	s_add_i32 s5, s4, s96
	s_cmp_lt_i32 s5, 0x4400
	s_cselect_b32 s5, s5, s4
	s_cselect_b32 s29, 1, 0
	s_waitcnt vmcnt(31)
	v_lshlrev_b32_e32 v199, 16, v4
	v_and_b32_e32 v200, 0xffff0000, v4
	v_lshlrev_b32_e32 v201, 16, v5
	v_and_b32_e32 v202, 0xffff0000, v5
	v_lshlrev_b32_e32 v203, 16, v6
	v_and_b32_e32 v204, 0xffff0000, v6
	v_lshlrev_b32_e32 v205, 16, v7
	v_and_b32_e32 v206, 0xffff0000, v7
	v_fma_f32 v191, v136, v199, 0
	v_fma_f32 v192, v136, v200, 0
	v_fma_f32 v193, v136, v201, 0
	v_fma_f32 v194, v136, v202, 0
	v_fma_f32 v195, v136, v203, 0
	v_fma_f32 v196, v136, v204, 0
	v_fma_f32 v197, v136, v205, 0
	v_fma_f32 v198, v136, v206, 0
	v_lshlrev_b32_e32 v199, 16, v8
	v_and_b32_e32 v200, 0xffff0000, v8
	v_lshlrev_b32_e32 v201, 16, v9
	v_and_b32_e32 v202, 0xffff0000, v9
	v_lshlrev_b32_e32 v203, 16, v10
	v_and_b32_e32 v204, 0xffff0000, v10
	v_lshlrev_b32_e32 v205, 16, v11
	v_and_b32_e32 v206, 0xffff0000, v11
	v_fma_f32 v191, v137, v199, v191
	v_fma_f32 v192, v137, v200, v192
	v_fma_f32 v193, v137, v201, v193
	v_fma_f32 v194, v137, v202, v194
	v_fma_f32 v195, v137, v203, v195
	v_fma_f32 v196, v137, v204, v196
	v_fma_f32 v197, v137, v205, v197
	v_fma_f32 v198, v137, v206, v198
	v_lshlrev_b32_e32 v199, 16, v0
	v_and_b32_e32 v200, 0xffff0000, v0
	v_lshlrev_b32_e32 v201, 16, v1
	v_and_b32_e32 v202, 0xffff0000, v1
	v_lshlrev_b32_e32 v203, 16, v2
	v_and_b32_e32 v204, 0xffff0000, v2
	v_lshlrev_b32_e32 v205, 16, v3
	v_and_b32_e32 v206, 0xffff0000, v3
	v_fma_f32 v191, v166, v191, -v199
	v_fma_f32 v192, v166, v192, -v200
	v_fma_f32 v193, v166, v193, -v201
	v_fma_f32 v194, v166, v194, -v202
	v_fma_f32 v195, v166, v195, -v203
	v_fma_f32 v196, v166, v196, -v204
	v_fma_f32 v197, v166, v197, -v205
	v_fma_f32 v198, v166, v198, -v206
	v_cvt_pk_bf16_f32 v208, v191, v192
	v_cvt_pk_bf16_f32 v209, v193, v194
	v_cvt_pk_bf16_f32 v210, v195, v196
	v_cvt_pk_bf16_f32 v211, v197, v198
	global_store_dwordx4 v175, v[208:211], s[24:25]
	s_mov_b32 s4, s5
	s_lshl_b32 s6, s4, 2
	s_cmp_lt_i32 s6, 0x10000
	s_cselect_b32 s26, 63, 0xff
	s_cselect_b32 s19, 64, 0x100
	s_and_b32 s18, s6, s26
	s_sub_i32 s27, s6, s18
	s_lshl_b32 s27, s27, 10
	v_add_u32_e32 v172, s18, v170
	v_add_u32_e32 v173, s27, v171
	v_subrev_u32_e32 v176, 1, v172
	v_add_u32_e32 v177, 1, v172
	v_max_i32_e32 v176, 0, v176
	v_min_i32_e32 v177, s19, v177
	v_lshl_add_u32 v187, v172, 10, v173
	v_sub_u32_e32 v178, v177, v176
	global_load_dwordx4 v[0:3], v187, s[22:23]
	v_lshl_add_u32 v188, v176, 10, v173
	v_mov_b32_e32 v136, 1.0
	global_load_dwordx4 v[4:7], v188, s[22:23]
	v_add_u32_e32 v179, 1, v176
	v_cmp_lt_i32_e64 s[30:31], v179, v177
	s_nop 1
	v_cndmask_b32_e64 v183, v172, v179, s[30:31]
	v_cndmask_b32_e64 v137, 0, 1.0, s[30:31]
	v_lshl_add_u32 v187, v183, 10, v173
	global_load_dwordx4 v[8:11], v187, s[22:23]
	v_cvt_f32_i32_e32 v178, v178
	v_div_scale_f32 v212, s[40:41], v178, v178, 1.0
	v_div_scale_f32 v215, vcc, 1.0, v178, 1.0
	v_rcp_f32_e32 v213, v212
	s_nop 0
	v_fma_f32 v214, -v212, v213, 1.0
	v_fmac_f32_e32 v213, v214, v213
	v_mul_f32_e32 v216, v215, v213
	v_fma_f32 v217, -v212, v216, v215
	v_fmac_f32_e32 v216, v217, v213
	v_fma_f32 v218, -v212, v216, v215
	v_div_fmas_f32 v219, v218, v213, v216
	v_div_fixup_f32 v166, v219, v178, 1.0
	s_waitcnt vmcnt(30)
	v_lshlrev_b32_e32 v199, 16, v16
	v_and_b32_e32 v200, 0xffff0000, v16
	v_lshlrev_b32_e32 v201, 16, v17
	v_and_b32_e32 v202, 0xffff0000, v17
	v_lshlrev_b32_e32 v203, 16, v18
	v_and_b32_e32 v204, 0xffff0000, v18
	v_lshlrev_b32_e32 v205, 16, v19
	v_and_b32_e32 v206, 0xffff0000, v19
	v_fma_f32 v191, v138, v199, 0
	v_fma_f32 v192, v138, v200, 0
	v_fma_f32 v193, v138, v201, 0
	v_fma_f32 v194, v138, v202, 0
	v_fma_f32 v195, v138, v203, 0
	v_fma_f32 v196, v138, v204, 0
	v_fma_f32 v197, v138, v205, 0
	v_fma_f32 v198, v138, v206, 0
	v_lshlrev_b32_e32 v199, 16, v20
	v_and_b32_e32 v200, 0xffff0000, v20
	v_lshlrev_b32_e32 v201, 16, v21
	v_and_b32_e32 v202, 0xffff0000, v21
	v_lshlrev_b32_e32 v203, 16, v22
	v_and_b32_e32 v204, 0xffff0000, v22
	v_lshlrev_b32_e32 v205, 16, v23
	v_and_b32_e32 v206, 0xffff0000, v23
	v_fma_f32 v191, v139, v199, v191
	v_fma_f32 v192, v139, v200, v192
	v_fma_f32 v193, v139, v201, v193
	v_fma_f32 v194, v139, v202, v194
	v_fma_f32 v195, v139, v203, v195
	v_fma_f32 v196, v139, v204, v196
	v_fma_f32 v197, v139, v205, v197
	v_fma_f32 v198, v139, v206, v198
	v_lshlrev_b32_e32 v199, 16, v24
	v_and_b32_e32 v200, 0xffff0000, v24
	v_lshlrev_b32_e32 v201, 16, v25
	v_and_b32_e32 v202, 0xffff0000, v25
	v_lshlrev_b32_e32 v203, 16, v26
	v_and_b32_e32 v204, 0xffff0000, v26
	v_lshlrev_b32_e32 v205, 16, v27
	v_and_b32_e32 v206, 0xffff0000, v27
	v_fma_f32 v191, v140, v199, v191
	v_fma_f32 v192, v140, v200, v192
	v_fma_f32 v193, v140, v201, v193
	v_fma_f32 v194, v140, v202, v194
	v_fma_f32 v195, v140, v203, v195
	v_fma_f32 v196, v140, v204, v196
	v_fma_f32 v197, v140, v205, v197
	v_fma_f32 v198, v140, v206, v198
	v_lshlrev_b32_e32 v199, 16, v28
	v_and_b32_e32 v200, 0xffff0000, v28
	v_lshlrev_b32_e32 v201, 16, v29
	v_and_b32_e32 v202, 0xffff0000, v29
	v_lshlrev_b32_e32 v203, 16, v30
	v_and_b32_e32 v204, 0xffff0000, v30
	v_lshlrev_b32_e32 v205, 16, v31
	v_and_b32_e32 v206, 0xffff0000, v31
	v_fma_f32 v191, v141, v199, v191
	v_fma_f32 v192, v141, v200, v192
	v_fma_f32 v193, v141, v201, v193
	v_fma_f32 v194, v141, v202, v194
	v_fma_f32 v195, v141, v203, v195
	v_fma_f32 v196, v141, v204, v196
	v_fma_f32 v197, v141, v205, v197
	v_fma_f32 v198, v141, v206, v198
	v_lshlrev_b32_e32 v199, 16, v12
	v_and_b32_e32 v200, 0xffff0000, v12
	v_lshlrev_b32_e32 v201, 16, v13
	v_and_b32_e32 v202, 0xffff0000, v13
; __device__ __forceinline__ unsigned cvtpk(float lo, float hi) { f32x2 v = {lo, hi}; bf16x2_t b = __builtin_convertvector(v, bf16x2_t); return __builtin_bit_cast(unsigned, b); }
; __device__ __forceinline__ float bflo(unsigned u) { return __uint_as_float(u << 16); }
; __device__ __forceinline__ float bfhi(unsigned u) { return __uint_as_float(u & 0xffff0000u); }
; template <int l> __device__ __forceinline__ void layer_body(LAS unsigned char* lds, const int wave_s) {
;     ...
;         for (int row = gw; row < rows_post; row += NGW) {
;             int pos, Ls; if (row < TL) { pos = row & 63; Ls = 64; } else { pos = (row - TL) & 255; Ls = 256; }
;             const int hw = 1 << (lane >> 4);
;             const int lo = max(pos - hw, 0), hi = min(pos + hw, Ls);
;             const bf16* base = POOLb + (size_t)(row - pos) * 512 + 8 * lane;
;             float s[8];
; #pragma unroll
;             for (int e = 0; e < 8; ++e) s[e] = 0.f;
;             v4u av[16];
; #pragma unroll
;             for (int k = 0; k < 16; ++k) { const int p = lo + k; const int pc = p < hi ? p : pos; av[k] = *(const v4u*)(base + (size_t)pc * 512); }
; #pragma unroll
;             for (int k = 0; k < 16; ++k) { const float vm = (lo + k < hi) ? 1.f : 0.f; const v4u a = av[k];
;                 s[0] += vm * bflo(a.x); s[1] += vm * bfhi(a.x); s[2] += vm * bflo(a.y); s[3] += vm * bfhi(a.y); s[4] += vm * bflo(a.z); s[5] += vm * bfhi(a.z); s[6] += vm * bflo(a.w); s[7] += vm * bfhi(a.w); }
;             const v4u me = *(const v4u*)(base + (size_t)pos * 512); const float inv = 1.0f / (float)(hi - lo);
;             v4u w; w.x = cvtpk(s[0] * inv - bflo(me.x), s[1] * inv - bfhi(me.x)); w.y = cvtpk(s[2] * inv - bflo(me.y), s[3] * inv - bfhi(me.y));
;             w.z = cvtpk(s[4] * inv - bflo(me.z), s[5] * inv - bfhi(me.z)); w.w = cvtpk(s[6] * inv - bflo(me.w), s[7] * inv - bfhi(me.w));
;             *(v4u*)(POOLEDb + (size_t)row * 512 + 8 * lane) = w;
	v_lshlrev_b32_e32 v203, 16, v14
	v_and_b32_e32 v204, 0xffff0000, v14
	v_lshlrev_b32_e32 v205, 16, v15
	v_and_b32_e32 v206, 0xffff0000, v15
	v_fma_f32 v191, v167, v191, -v199
	v_fma_f32 v192, v167, v192, -v200
	v_fma_f32 v193, v167, v193, -v201
	v_fma_f32 v194, v167, v194, -v202
	v_fma_f32 v195, v167, v195, -v203
	v_fma_f32 v196, v167, v196, -v204
	v_fma_f32 v197, v167, v197, -v205
	v_fma_f32 v198, v167, v198, -v206
	v_cvt_pk_bf16_f32 v208, v191, v192
	v_cvt_pk_bf16_f32 v209, v193, v194
	v_cvt_pk_bf16_f32 v210, v195, v196
	v_cvt_pk_bf16_f32 v211, v197, v198
	global_store_dwordx4 v175, v[208:211], s[24:25] offset:256
	v_subrev_u32_e32 v176, 2, v172
	v_add_u32_e32 v177, 2, v172
	v_max_i32_e32 v176, 0, v176
	v_min_i32_e32 v177, s19, v177
	v_lshl_add_u32 v187, v172, 10, v173
	v_sub_u32_e32 v178, v177, v176
	global_load_dwordx4 v[12:15], v187, s[22:23] offset:256
	v_lshl_add_u32 v188, v176, 10, v173
	v_mov_b32_e32 v138, 1.0
	global_load_dwordx4 v[16:19], v188, s[22:23] offset:256
	v_add_u32_e32 v179, 1, v176
	v_add_u32_e32 v180, 2, v176
	v_add_u32_e32 v181, 3, v176
	v_cmp_lt_i32_e64 s[30:31], v179, v177
	v_cmp_lt_i32_e64 s[34:35], v180, v177
	v_cmp_lt_i32_e64 s[36:37], v181, v177
	v_cndmask_b32_e64 v183, v172, v179, s[30:31]
	v_cndmask_b32_e64 v139, 0, 1.0, s[30:31]
	v_lshl_add_u32 v187, v183, 10, v173
	global_load_dwordx4 v[20:23], v187, s[22:23] offset:256
	v_cndmask_b32_e64 v184, v172, v180, s[34:35]
	v_cndmask_b32_e64 v140, 0, 1.0, s[34:35]
	v_lshl_add_u32 v188, v184, 10, v173
	global_load_dwordx4 v[24:27], v188, s[22:23] offset:256
	v_cndmask_b32_e64 v185, v172, v181, s[36:37]
	v_cndmask_b32_e64 v141, 0, 1.0, s[36:37]
	v_lshl_add_u32 v189, v185, 10, v173
	global_load_dwordx4 v[28:31], v189, s[22:23] offset:256
	v_cvt_f32_i32_e32 v178, v178
	v_div_scale_f32 v212, s[40:41], v178, v178, 1.0
	v_div_scale_f32 v215, vcc, 1.0, v178, 1.0
	v_rcp_f32_e32 v213, v212
	s_nop 0
	v_fma_f32 v214, -v212, v213, 1.0
	v_fmac_f32_e32 v213, v214, v213
	v_mul_f32_e32 v216, v215, v213
	v_fma_f32 v217, -v212, v216, v215
	v_fmac_f32_e32 v216, v217, v213
	v_fma_f32 v218, -v212, v216, v215
	v_div_fmas_f32 v219, v218, v213, v216
	v_div_fixup_f32 v167, v219, v178, 1.0
	s_waitcnt vmcnt(27)
	v_lshlrev_b32_e32 v199, 16, v36
	v_and_b32_e32 v200, 0xffff0000, v36
	v_lshlrev_b32_e32 v201, 16, v37
	v_and_b32_e32 v202, 0xffff0000, v37
	v_lshlrev_b32_e32 v203, 16, v38
	v_and_b32_e32 v204, 0xffff0000, v38
	v_lshlrev_b32_e32 v205, 16, v39
	v_and_b32_e32 v206, 0xffff0000, v39
	v_fma_f32 v191, v142, v199, 0
	v_fma_f32 v192, v142, v200, 0
	v_fma_f32 v193, v142, v201, 0
	v_fma_f32 v194, v142, v202, 0
	v_fma_f32 v195, v142, v203, 0
	v_fma_f32 v196, v142, v204, 0
	v_fma_f32 v197, v142, v205, 0
	v_fma_f32 v198, v142, v206, 0
	v_lshlrev_b32_e32 v199, 16, v40
	v_and_b32_e32 v200, 0xffff0000, v40
	v_lshlrev_b32_e32 v201, 16, v41
	v_and_b32_e32 v202, 0xffff0000, v41
	v_lshlrev_b32_e32 v203, 16, v42
	v_and_b32_e32 v204, 0xffff0000, v42
	v_lshlrev_b32_e32 v205, 16, v43
	v_and_b32_e32 v206, 0xffff0000, v43
	v_fma_f32 v191, v143, v199, v191
	v_fma_f32 v192, v143, v200, v192
	v_fma_f32 v193, v143, v201, v193
	v_fma_f32 v194, v143, v202, v194
	v_fma_f32 v195, v143, v203, v195
	v_fma_f32 v196, v143, v204, v196
	v_fma_f32 v197, v143, v205, v197
	v_fma_f32 v198, v143, v206, v198
	v_lshlrev_b32_e32 v199, 16, v44
	v_and_b32_e32 v200, 0xffff0000, v44
	v_lshlrev_b32_e32 v201, 16, v45
	v_and_b32_e32 v202, 0xffff0000, v45
	v_lshlrev_b32_e32 v203, 16, v46
	v_and_b32_e32 v204, 0xffff0000, v46
	v_lshlrev_b32_e32 v205, 16, v47
	v_and_b32_e32 v206, 0xffff0000, v47
	v_fma_f32 v191, v144, v199, v191
	v_fma_f32 v192, v144, v200, v192
	v_fma_f32 v193, v144, v201, v193
	v_fma_f32 v194, v144, v202, v194
	v_fma_f32 v195, v144, v203, v195
	v_fma_f32 v196, v144, v204, v196
	v_fma_f32 v197, v144, v205, v197
	v_fma_f32 v198, v144, v206, v198
	v_lshlrev_b32_e32 v199, 16, v48
	v_and_b32_e32 v200, 0xffff0000, v48
	v_lshlrev_b32_e32 v201, 16, v49
	v_and_b32_e32 v202, 0xffff0000, v49
	v_lshlrev_b32_e32 v203, 16, v50
	v_and_b32_e32 v204, 0xffff0000, v50
	v_lshlrev_b32_e32 v205, 16, v51
	v_and_b32_e32 v206, 0xffff0000, v51
	v_fma_f32 v191, v145, v199, v191
	v_fma_f32 v192, v145, v200, v192
	v_fma_f32 v193, v145, v201, v193
	v_fma_f32 v194, v145, v202, v194
	v_fma_f32 v195, v145, v203, v195
	v_fma_f32 v196, v145, v204, v196
	v_fma_f32 v197, v145, v205, v197
	v_fma_f32 v198, v145, v206, v198
	v_lshlrev_b32_e32 v199, 16, v52
	v_and_b32_e32 v200, 0xffff0000, v52
	v_lshlrev_b32_e32 v201, 16, v53
	v_and_b32_e32 v202, 0xffff0000, v53
	v_lshlrev_b32_e32 v203, 16, v54
	v_and_b32_e32 v204, 0xffff0000, v54
	v_lshlrev_b32_e32 v205, 16, v55
	v_and_b32_e32 v206, 0xffff0000, v55
	v_fma_f32 v191, v146, v199, v191
	v_fma_f32 v192, v146, v200, v192
	v_fma_f32 v193, v146, v201, v193
	v_fma_f32 v194, v146, v202, v194
	v_fma_f32 v195, v146, v203, v195
	v_fma_f32 v196, v146, v204, v196
	v_fma_f32 v197, v146, v205, v197
	v_fma_f32 v198, v146, v206, v198
	v_lshlrev_b32_e32 v199, 16, v56
	v_and_b32_e32 v200, 0xffff0000, v56
	v_lshlrev_b32_e32 v201, 16, v57
	v_and_b32_e32 v202, 0xffff0000, v57
	v_lshlrev_b32_e32 v203, 16, v58
	v_and_b32_e32 v204, 0xffff0000, v58
	v_lshlrev_b32_e32 v205, 16, v59
	v_and_b32_e32 v206, 0xffff0000, v59
	v_fma_f32 v191, v147, v199, v191
	v_fma_f32 v192, v147, v200, v192
	v_fma_f32 v193, v147, v201, v193
	v_fma_f32 v194, v147, v202, v194
	v_fma_f32 v195, v147, v203, v195
	v_fma_f32 v196, v147, v204, v196
	v_fma_f32 v197, v147, v205, v197
	v_fma_f32 v198, v147, v206, v198
	v_lshlrev_b32_e32 v199, 16, v60
	v_and_b32_e32 v200, 0xffff0000, v60
	v_lshlrev_b32_e32 v201, 16, v61
	v_and_b32_e32 v202, 0xffff0000, v61
; __device__ __forceinline__ unsigned cvtpk(float lo, float hi) { f32x2 v = {lo, hi}; bf16x2_t b = __builtin_convertvector(v, bf16x2_t); return __builtin_bit_cast(unsigned, b); }
; __device__ __forceinline__ float bflo(unsigned u) { return __uint_as_float(u << 16); }
; __device__ __forceinline__ float bfhi(unsigned u) { return __uint_as_float(u & 0xffff0000u); }
; template <int l> __device__ __forceinline__ void layer_body(LAS unsigned char* lds, const int wave_s) {
;     ...
;         for (int row = gw; row < rows_post; row += NGW) {
;             int pos, Ls; if (row < TL) { pos = row & 63; Ls = 64; } else { pos = (row - TL) & 255; Ls = 256; }
;             const int hw = 1 << (lane >> 4);
;             const int lo = max(pos - hw, 0), hi = min(pos + hw, Ls);
;             const bf16* base = POOLb + (size_t)(row - pos) * 512 + 8 * lane;
;             float s[8];
; #pragma unroll
;             for (int e = 0; e < 8; ++e) s[e] = 0.f;
;             v4u av[16];
; #pragma unroll
;             for (int k = 0; k < 16; ++k) { const int p = lo + k; const int pc = p < hi ? p : pos; av[k] = *(const v4u*)(base + (size_t)pc * 512); }
; #pragma unroll
;             for (int k = 0; k < 16; ++k) { const float vm = (lo + k < hi) ? 1.f : 0.f; const v4u a = av[k];
;                 s[0] += vm * bflo(a.x); s[1] += vm * bfhi(a.x); s[2] += vm * bflo(a.y); s[3] += vm * bfhi(a.y); s[4] += vm * bflo(a.z); s[5] += vm * bfhi(a.z); s[6] += vm * bflo(a.w); s[7] += vm * bfhi(a.w); }
;             const v4u me = *(const v4u*)(base + (size_t)pos * 512); const float inv = 1.0f / (float)(hi - lo);
;             v4u w; w.x = cvtpk(s[0] * inv - bflo(me.x), s[1] * inv - bfhi(me.x)); w.y = cvtpk(s[2] * inv - bflo(me.y), s[3] * inv - bfhi(me.y));
;             w.z = cvtpk(s[4] * inv - bflo(me.z), s[5] * inv - bfhi(me.z)); w.w = cvtpk(s[6] * inv - bflo(me.w), s[7] * inv - bfhi(me.w));
;             *(v4u*)(POOLEDb + (size_t)row * 512 + 8 * lane) = w;
	v_lshlrev_b32_e32 v203, 16, v62
	v_and_b32_e32 v204, 0xffff0000, v62
	v_lshlrev_b32_e32 v205, 16, v63
	v_and_b32_e32 v206, 0xffff0000, v63
	v_fma_f32 v191, v148, v199, v191
	v_fma_f32 v192, v148, v200, v192
	v_fma_f32 v193, v148, v201, v193
	v_fma_f32 v194, v148, v202, v194
	v_fma_f32 v195, v148, v203, v195
	v_fma_f32 v196, v148, v204, v196
	v_fma_f32 v197, v148, v205, v197
	v_fma_f32 v198, v148, v206, v198
	v_lshlrev_b32_e32 v199, 16, v64
	v_and_b32_e32 v200, 0xffff0000, v64
	v_lshlrev_b32_e32 v201, 16, v65
	v_and_b32_e32 v202, 0xffff0000, v65
	v_lshlrev_b32_e32 v203, 16, v66
	v_and_b32_e32 v204, 0xffff0000, v66
	v_lshlrev_b32_e32 v205, 16, v67
	v_and_b32_e32 v206, 0xffff0000, v67
	v_fma_f32 v191, v149, v199, v191
	v_fma_f32 v192, v149, v200, v192
	v_fma_f32 v193, v149, v201, v193
	v_fma_f32 v194, v149, v202, v194
	v_fma_f32 v195, v149, v203, v195
	v_fma_f32 v196, v149, v204, v196
	v_fma_f32 v197, v149, v205, v197
	v_fma_f32 v198, v149, v206, v198
	v_lshlrev_b32_e32 v199, 16, v32
	v_and_b32_e32 v200, 0xffff0000, v32
	v_lshlrev_b32_e32 v201, 16, v33
	v_and_b32_e32 v202, 0xffff0000, v33
	v_lshlrev_b32_e32 v203, 16, v34
	v_and_b32_e32 v204, 0xffff0000, v34
	v_lshlrev_b32_e32 v205, 16, v35
	v_and_b32_e32 v206, 0xffff0000, v35
	v_fma_f32 v191, v168, v191, -v199
	v_fma_f32 v192, v168, v192, -v200
	v_fma_f32 v193, v168, v193, -v201
	v_fma_f32 v194, v168, v194, -v202
	v_fma_f32 v195, v168, v195, -v203
	v_fma_f32 v196, v168, v196, -v204
	v_fma_f32 v197, v168, v197, -v205
	v_fma_f32 v198, v168, v198, -v206
	v_cvt_pk_bf16_f32 v208, v191, v192
	v_cvt_pk_bf16_f32 v209, v193, v194
	v_cvt_pk_bf16_f32 v210, v195, v196
	v_cvt_pk_bf16_f32 v211, v197, v198
	global_store_dwordx4 v175, v[208:211], s[24:25] offset:512
	v_subrev_u32_e32 v176, 4, v172
	v_add_u32_e32 v177, 4, v172
	v_max_i32_e32 v176, 0, v176
	v_min_i32_e32 v177, s19, v177
	v_lshl_add_u32 v187, v172, 10, v173
	v_sub_u32_e32 v178, v177, v176
	global_load_dwordx4 v[32:35], v187, s[22:23] offset:512
	v_lshl_add_u32 v188, v176, 10, v173
	v_mov_b32_e32 v142, 1.0
	global_load_dwordx4 v[36:39], v188, s[22:23] offset:512
	v_add_u32_e32 v179, 1, v176
	v_add_u32_e32 v180, 2, v176
	v_add_u32_e32 v181, 3, v176
	v_add_u32_e32 v182, 4, v176
	v_cmp_lt_i32_e64 s[30:31], v179, v177
	v_cmp_lt_i32_e64 s[34:35], v180, v177
	v_cmp_lt_i32_e64 s[36:37], v181, v177
	v_cmp_lt_i32_e64 s[38:39], v182, v177
	v_cndmask_b32_e64 v183, v172, v179, s[30:31]
	v_cndmask_b32_e64 v143, 0, 1.0, s[30:31]
	v_lshl_add_u32 v187, v183, 10, v173
	global_load_dwordx4 v[40:43], v187, s[22:23] offset:512
	v_cndmask_b32_e64 v184, v172, v180, s[34:35]
	v_cndmask_b32_e64 v144, 0, 1.0, s[34:35]
	v_lshl_add_u32 v188, v184, 10, v173
	global_load_dwordx4 v[44:47], v188, s[22:23] offset:512
	v_cndmask_b32_e64 v185, v172, v181, s[36:37]
	v_cndmask_b32_e64 v145, 0, 1.0, s[36:37]
	v_lshl_add_u32 v189, v185, 10, v173
	global_load_dwordx4 v[48:51], v189, s[22:23] offset:512
	v_cndmask_b32_e64 v186, v172, v182, s[38:39]
	v_cndmask_b32_e64 v146, 0, 1.0, s[38:39]
	v_lshl_add_u32 v190, v186, 10, v173
	global_load_dwordx4 v[52:55], v190, s[22:23] offset:512
	v_add_u32_e32 v179, 5, v176
	v_add_u32_e32 v180, 6, v176
	v_add_u32_e32 v181, 7, v176
	v_cmp_lt_i32_e64 s[30:31], v179, v177
	v_cmp_lt_i32_e64 s[34:35], v180, v177
	v_cmp_lt_i32_e64 s[36:37], v181, v177
	v_cndmask_b32_e64 v183, v172, v179, s[30:31]
	v_cndmask_b32_e64 v147, 0, 1.0, s[30:31]
	v_lshl_add_u32 v187, v183, 10, v173
	global_load_dwordx4 v[56:59], v187, s[22:23] offset:512
	v_cndmask_b32_e64 v184, v172, v180, s[34:35]
	v_cndmask_b32_e64 v148, 0, 1.0, s[34:35]
	v_lshl_add_u32 v188, v184, 10, v173
	global_load_dwordx4 v[60:63], v188, s[22:23] offset:512
	v_cndmask_b32_e64 v185, v172, v181, s[36:37]
	v_cndmask_b32_e64 v149, 0, 1.0, s[36:37]
	v_lshl_add_u32 v189, v185, 10, v173
	global_load_dwordx4 v[64:67], v189, s[22:23] offset:512
	v_cvt_f32_i32_e32 v178, v178
	v_div_scale_f32 v212, s[40:41], v178, v178, 1.0
	v_div_scale_f32 v215, vcc, 1.0, v178, 1.0
	v_rcp_f32_e32 v213, v212
	s_nop 0
	v_fma_f32 v214, -v212, v213, 1.0
	v_fmac_f32_e32 v213, v214, v213
	v_mul_f32_e32 v216, v215, v213
	v_fma_f32 v217, -v212, v216, v215
	v_fmac_f32_e32 v216, v217, v213
	v_fma_f32 v218, -v212, v216, v215
	v_div_fmas_f32 v219, v218, v213, v216
	v_div_fixup_f32 v168, v219, v178, 1.0
	s_waitcnt vmcnt(20)
; __device__ __forceinline__ float bflo(unsigned u) { return __uint_as_float(u << 16); }
; __device__ __forceinline__ float bfhi(unsigned u) { return __uint_as_float(u & 0xffff0000u); }
; template <int l> __device__ __forceinline__ void layer_body(LAS unsigned char* lds, const int wave_s) {
;     ...
;             for (int k = 0; k < 16; ++k) { const float vm = (lo + k < hi) ? 1.f : 0.f; const v4u a = av[k];
;                 s[0] += vm * bflo(a.x); s[1] += vm * bfhi(a.x); s[2] += vm * bflo(a.y); s[3] += vm * bfhi(a.y); s[4] += vm * bflo(a.z); s[5] += vm * bfhi(a.z); s[6] += vm * bflo(a.w); s[7] += vm * bfhi(a.w); }
	v_lshlrev_b32_e32 v199, 16, v72
	v_and_b32_e32 v200, 0xffff0000, v72
	v_lshlrev_b32_e32 v201, 16, v73
	v_and_b32_e32 v202, 0xffff0000, v73
	v_lshlrev_b32_e32 v203, 16, v74
	v_and_b32_e32 v204, 0xffff0000, v74
	v_lshlrev_b32_e32 v205, 16, v75
	v_and_b32_e32 v206, 0xffff0000, v75
	v_fma_f32 v191, v150, v199, 0
	v_fma_f32 v192, v150, v200, 0
	v_fma_f32 v193, v150, v201, 0
	v_fma_f32 v194, v150, v202, 0
	v_fma_f32 v195, v150, v203, 0
	v_fma_f32 v196, v150, v204, 0
	v_fma_f32 v197, v150, v205, 0
	v_fma_f32 v198, v150, v206, 0
	v_lshlrev_b32_e32 v199, 16, v76
	v_and_b32_e32 v200, 0xffff0000, v76
	v_lshlrev_b32_e32 v201, 16, v77
	v_and_b32_e32 v202, 0xffff0000, v77
	v_lshlrev_b32_e32 v203, 16, v78
	v_and_b32_e32 v204, 0xffff0000, v78
	v_lshlrev_b32_e32 v205, 16, v79
	v_and_b32_e32 v206, 0xffff0000, v79
	v_fma_f32 v191, v151, v199, v191
	v_fma_f32 v192, v151, v200, v192
	v_fma_f32 v193, v151, v201, v193
	v_fma_f32 v194, v151, v202, v194
	v_fma_f32 v195, v151, v203, v195
	v_fma_f32 v196, v151, v204, v196
	v_fma_f32 v197, v151, v205, v197
	v_fma_f32 v198, v151, v206, v198
	v_lshlrev_b32_e32 v199, 16, v80
	v_and_b32_e32 v200, 0xffff0000, v80
	v_lshlrev_b32_e32 v201, 16, v81
	v_and_b32_e32 v202, 0xffff0000, v81
	v_lshlrev_b32_e32 v203, 16, v82
	v_and_b32_e32 v204, 0xffff0000, v82
	v_lshlrev_b32_e32 v205, 16, v83
	v_and_b32_e32 v206, 0xffff0000, v83
	v_fma_f32 v191, v152, v199, v191
	v_fma_f32 v192, v152, v200, v192
	v_fma_f32 v193, v152, v201, v193
	v_fma_f32 v194, v152, v202, v194
	v_fma_f32 v195, v152, v203, v195
	v_fma_f32 v196, v152, v204, v196
	v_fma_f32 v197, v152, v205, v197
	v_fma_f32 v198, v152, v206, v198
	v_lshlrev_b32_e32 v199, 16, v84
	v_and_b32_e32 v200, 0xffff0000, v84
	v_lshlrev_b32_e32 v201, 16, v85
	v_and_b32_e32 v202, 0xffff0000, v85
	v_lshlrev_b32_e32 v203, 16, v86
	v_and_b32_e32 v204, 0xffff0000, v86
	v_lshlrev_b32_e32 v205, 16, v87
	v_and_b32_e32 v206, 0xffff0000, v87
	v_fma_f32 v191, v153, v199, v191
	v_fma_f32 v192, v153, v200, v192
	v_fma_f32 v193, v153, v201, v193
	v_fma_f32 v194, v153, v202, v194
	v_fma_f32 v195, v153, v203, v195
	v_fma_f32 v196, v153, v204, v196
	v_fma_f32 v197, v153, v205, v197
	v_fma_f32 v198, v153, v206, v198
	v_lshlrev_b32_e32 v199, 16, v88
	v_and_b32_e32 v200, 0xffff0000, v88
	v_lshlrev_b32_e32 v201, 16, v89
	v_and_b32_e32 v202, 0xffff0000, v89
	v_lshlrev_b32_e32 v203, 16, v90
	v_and_b32_e32 v204, 0xffff0000, v90
	v_lshlrev_b32_e32 v205, 16, v91
	v_and_b32_e32 v206, 0xffff0000, v91
	v_fma_f32 v191, v154, v199, v191
	v_fma_f32 v192, v154, v200, v192
	v_fma_f32 v193, v154, v201, v193
	v_fma_f32 v194, v154, v202, v194
	v_fma_f32 v195, v154, v203, v195
	v_fma_f32 v196, v154, v204, v196
	v_fma_f32 v197, v154, v205, v197
	v_fma_f32 v198, v154, v206, v198
	v_lshlrev_b32_e32 v199, 16, v92
	v_and_b32_e32 v200, 0xffff0000, v92
	v_lshlrev_b32_e32 v201, 16, v93
	v_and_b32_e32 v202, 0xffff0000, v93
	v_lshlrev_b32_e32 v203, 16, v94
	v_and_b32_e32 v204, 0xffff0000, v94
	v_lshlrev_b32_e32 v205, 16, v95
	v_and_b32_e32 v206, 0xffff0000, v95
	v_fma_f32 v191, v155, v199, v191
	v_fma_f32 v192, v155, v200, v192
	v_fma_f32 v193, v155, v201, v193
	v_fma_f32 v194, v155, v202, v194
	v_fma_f32 v195, v155, v203, v195
	v_fma_f32 v196, v155, v204, v196
	v_fma_f32 v197, v155, v205, v197
	v_fma_f32 v198, v155, v206, v198
	v_lshlrev_b32_e32 v199, 16, v96
	v_and_b32_e32 v200, 0xffff0000, v96
	v_lshlrev_b32_e32 v201, 16, v97
	v_and_b32_e32 v202, 0xffff0000, v97
	v_lshlrev_b32_e32 v203, 16, v98
	v_and_b32_e32 v204, 0xffff0000, v98
	v_lshlrev_b32_e32 v205, 16, v99
	v_and_b32_e32 v206, 0xffff0000, v99
	v_fma_f32 v191, v156, v199, v191
	v_fma_f32 v192, v156, v200, v192
	v_fma_f32 v193, v156, v201, v193
	v_fma_f32 v194, v156, v202, v194
	v_fma_f32 v195, v156, v203, v195
	v_fma_f32 v196, v156, v204, v196
	v_fma_f32 v197, v156, v205, v197
	v_fma_f32 v198, v156, v206, v198
	v_lshlrev_b32_e32 v199, 16, v100
	v_and_b32_e32 v200, 0xffff0000, v100
	v_lshlrev_b32_e32 v201, 16, v101
	v_and_b32_e32 v202, 0xffff0000, v101
	v_lshlrev_b32_e32 v203, 16, v102
	v_and_b32_e32 v204, 0xffff0000, v102
	v_lshlrev_b32_e32 v205, 16, v103
	v_and_b32_e32 v206, 0xffff0000, v103
	v_fma_f32 v191, v157, v199, v191
	v_fma_f32 v192, v157, v200, v192
	v_fma_f32 v193, v157, v201, v193
	v_fma_f32 v194, v157, v202, v194
	v_fma_f32 v195, v157, v203, v195
	v_fma_f32 v196, v157, v204, v196
	v_fma_f32 v197, v157, v205, v197
	v_fma_f32 v198, v157, v206, v198
	v_lshlrev_b32_e32 v199, 16, v104
	v_and_b32_e32 v200, 0xffff0000, v104
	v_lshlrev_b32_e32 v201, 16, v105
	v_and_b32_e32 v202, 0xffff0000, v105
	v_lshlrev_b32_e32 v203, 16, v106
	v_and_b32_e32 v204, 0xffff0000, v106
	v_lshlrev_b32_e32 v205, 16, v107
	v_and_b32_e32 v206, 0xffff0000, v107
	v_fma_f32 v191, v158, v199, v191
	v_fma_f32 v192, v158, v200, v192
	v_fma_f32 v193, v158, v201, v193
	v_fma_f32 v194, v158, v202, v194
	v_fma_f32 v195, v158, v203, v195
	v_fma_f32 v196, v158, v204, v196
	v_fma_f32 v197, v158, v205, v197
	v_fma_f32 v198, v158, v206, v198
	v_lshlrev_b32_e32 v199, 16, v108
	v_and_b32_e32 v200, 0xffff0000, v108
	v_lshlrev_b32_e32 v201, 16, v109
	v_and_b32_e32 v202, 0xffff0000, v109
	v_lshlrev_b32_e32 v203, 16, v110
	v_and_b32_e32 v204, 0xffff0000, v110
	v_lshlrev_b32_e32 v205, 16, v111
	v_and_b32_e32 v206, 0xffff0000, v111
	v_fma_f32 v191, v159, v199, v191
	v_fma_f32 v192, v159, v200, v192
	v_fma_f32 v193, v159, v201, v193
	v_fma_f32 v194, v159, v202, v194
	v_fma_f32 v195, v159, v203, v195
	v_fma_f32 v196, v159, v204, v196
	v_fma_f32 v197, v159, v205, v197
	v_fma_f32 v198, v159, v206, v198
	v_lshlrev_b32_e32 v199, 16, v112
	v_and_b32_e32 v200, 0xffff0000, v112
	v_lshlrev_b32_e32 v201, 16, v113
; __device__ __forceinline__ unsigned cvtpk(float lo, float hi) { f32x2 v = {lo, hi}; bf16x2_t b = __builtin_convertvector(v, bf16x2_t); return __builtin_bit_cast(unsigned, b); }
; __device__ __forceinline__ float bflo(unsigned u) { return __uint_as_float(u << 16); }
; __device__ __forceinline__ float bfhi(unsigned u) { return __uint_as_float(u & 0xffff0000u); }
; template <int l> __device__ __forceinline__ void layer_body(LAS unsigned char* lds, const int wave_s) {
;     ...
;             for (int k = 0; k < 16; ++k) { const float vm = (lo + k < hi) ? 1.f : 0.f; const v4u a = av[k];
;                 s[0] += vm * bflo(a.x); s[1] += vm * bfhi(a.x); s[2] += vm * bflo(a.y); s[3] += vm * bfhi(a.y); s[4] += vm * bflo(a.z); s[5] += vm * bfhi(a.z); s[6] += vm * bflo(a.w); s[7] += vm * bfhi(a.w); }
;             const v4u me = *(const v4u*)(base + (size_t)pos * 512); const float inv = 1.0f / (float)(hi - lo);
;             v4u w; w.x = cvtpk(s[0] * inv - bflo(me.x), s[1] * inv - bfhi(me.x)); w.y = cvtpk(s[2] * inv - bflo(me.y), s[3] * inv - bfhi(me.y));
;             w.z = cvtpk(s[4] * inv - bflo(me.z), s[5] * inv - bfhi(me.z)); w.w = cvtpk(s[6] * inv - bflo(me.w), s[7] * inv - bfhi(me.w));
;             *(v4u*)(POOLEDb + (size_t)row * 512 + 8 * lane) = w;
	v_and_b32_e32 v202, 0xffff0000, v113
	v_lshlrev_b32_e32 v203, 16, v114
	v_and_b32_e32 v204, 0xffff0000, v114
	v_lshlrev_b32_e32 v205, 16, v115
	v_and_b32_e32 v206, 0xffff0000, v115
	v_fma_f32 v191, v160, v199, v191
	v_fma_f32 v192, v160, v200, v192
	v_fma_f32 v193, v160, v201, v193
	v_fma_f32 v194, v160, v202, v194
	v_fma_f32 v195, v160, v203, v195
	v_fma_f32 v196, v160, v204, v196
	v_fma_f32 v197, v160, v205, v197
	v_fma_f32 v198, v160, v206, v198
	v_lshlrev_b32_e32 v199, 16, v116
	v_and_b32_e32 v200, 0xffff0000, v116
	v_lshlrev_b32_e32 v201, 16, v117
	v_and_b32_e32 v202, 0xffff0000, v117
	v_lshlrev_b32_e32 v203, 16, v118
	v_and_b32_e32 v204, 0xffff0000, v118
	v_lshlrev_b32_e32 v205, 16, v119
	v_and_b32_e32 v206, 0xffff0000, v119
	v_fma_f32 v191, v161, v199, v191
	v_fma_f32 v192, v161, v200, v192
	v_fma_f32 v193, v161, v201, v193
	v_fma_f32 v194, v161, v202, v194
	v_fma_f32 v195, v161, v203, v195
	v_fma_f32 v196, v161, v204, v196
	v_fma_f32 v197, v161, v205, v197
	v_fma_f32 v198, v161, v206, v198
	v_lshlrev_b32_e32 v199, 16, v120
	v_and_b32_e32 v200, 0xffff0000, v120
	v_lshlrev_b32_e32 v201, 16, v121
	v_and_b32_e32 v202, 0xffff0000, v121
	v_lshlrev_b32_e32 v203, 16, v122
	v_and_b32_e32 v204, 0xffff0000, v122
	v_lshlrev_b32_e32 v205, 16, v123
	v_and_b32_e32 v206, 0xffff0000, v123
	v_fma_f32 v191, v162, v199, v191
	v_fma_f32 v192, v162, v200, v192
	v_fma_f32 v193, v162, v201, v193
	v_fma_f32 v194, v162, v202, v194
	v_fma_f32 v195, v162, v203, v195
	v_fma_f32 v196, v162, v204, v196
	v_fma_f32 v197, v162, v205, v197
	v_fma_f32 v198, v162, v206, v198
	v_lshlrev_b32_e32 v199, 16, v124
	v_and_b32_e32 v200, 0xffff0000, v124
	v_lshlrev_b32_e32 v201, 16, v125
	v_and_b32_e32 v202, 0xffff0000, v125
	v_lshlrev_b32_e32 v203, 16, v126
	v_and_b32_e32 v204, 0xffff0000, v126
	v_lshlrev_b32_e32 v205, 16, v127
	v_and_b32_e32 v206, 0xffff0000, v127
	v_fma_f32 v191, v163, v199, v191
	v_fma_f32 v192, v163, v200, v192
	v_fma_f32 v193, v163, v201, v193
	v_fma_f32 v194, v163, v202, v194
	v_fma_f32 v195, v163, v203, v195
	v_fma_f32 v196, v163, v204, v196
	v_fma_f32 v197, v163, v205, v197
	v_fma_f32 v198, v163, v206, v198
	v_lshlrev_b32_e32 v199, 16, v128
	v_and_b32_e32 v200, 0xffff0000, v128
	v_lshlrev_b32_e32 v201, 16, v129
	v_and_b32_e32 v202, 0xffff0000, v129
	v_lshlrev_b32_e32 v203, 16, v130
	v_and_b32_e32 v204, 0xffff0000, v130
	v_lshlrev_b32_e32 v205, 16, v131
	v_and_b32_e32 v206, 0xffff0000, v131
	v_fma_f32 v191, v164, v199, v191
	v_fma_f32 v192, v164, v200, v192
	v_fma_f32 v193, v164, v201, v193
	v_fma_f32 v194, v164, v202, v194
	v_fma_f32 v195, v164, v203, v195
	v_fma_f32 v196, v164, v204, v196
	v_fma_f32 v197, v164, v205, v197
	v_fma_f32 v198, v164, v206, v198
	v_lshlrev_b32_e32 v199, 16, v132
	v_and_b32_e32 v200, 0xffff0000, v132
	v_lshlrev_b32_e32 v201, 16, v133
	v_and_b32_e32 v202, 0xffff0000, v133
	v_lshlrev_b32_e32 v203, 16, v134
	v_and_b32_e32 v204, 0xffff0000, v134
	v_lshlrev_b32_e32 v205, 16, v135
	v_and_b32_e32 v206, 0xffff0000, v135
	v_fma_f32 v191, v165, v199, v191
	v_fma_f32 v192, v165, v200, v192
	v_fma_f32 v193, v165, v201, v193
	v_fma_f32 v194, v165, v202, v194
	v_fma_f32 v195, v165, v203, v195
	v_fma_f32 v196, v165, v204, v196
	v_fma_f32 v197, v165, v205, v197
	v_fma_f32 v198, v165, v206, v198
	v_lshlrev_b32_e32 v199, 16, v68
	v_and_b32_e32 v200, 0xffff0000, v68
	v_lshlrev_b32_e32 v201, 16, v69
	v_and_b32_e32 v202, 0xffff0000, v69
	v_lshlrev_b32_e32 v203, 16, v70
	v_and_b32_e32 v204, 0xffff0000, v70
	v_lshlrev_b32_e32 v205, 16, v71
	v_and_b32_e32 v206, 0xffff0000, v71
	v_fma_f32 v191, v169, v191, -v199
	v_fma_f32 v192, v169, v192, -v200
	v_fma_f32 v193, v169, v193, -v201
	v_fma_f32 v194, v169, v194, -v202
	v_fma_f32 v195, v169, v195, -v203
	v_fma_f32 v196, v169, v196, -v204
	v_fma_f32 v197, v169, v197, -v205
	v_fma_f32 v198, v169, v198, -v206
	v_cvt_pk_bf16_f32 v208, v191, v192
	v_cvt_pk_bf16_f32 v209, v193, v194
	v_cvt_pk_bf16_f32 v210, v195, v196
	v_cvt_pk_bf16_f32 v211, v197, v198
	global_store_dwordx4 v175, v[208:211], s[24:25] offset:768
	v_subrev_u32_e32 v176, 8, v172
	v_add_u32_e32 v177, 8, v172
	v_max_i32_e32 v176, 0, v176
	v_min_i32_e32 v177, s19, v177
	v_lshl_add_u32 v187, v172, 10, v173
	v_sub_u32_e32 v178, v177, v176
	global_load_dwordx4 v[68:71], v187, s[22:23] offset:768
	v_lshl_add_u32 v188, v176, 10, v173
	v_mov_b32_e32 v150, 1.0
; template <int l> __device__ __forceinline__ void layer_body(LAS unsigned char* lds, const int wave_s) {
;     ...
;         for (int row = gw; row < rows_post; row += NGW) {
;             int pos, Ls; if (row < TL) { pos = row & 63; Ls = 64; } else { pos = (row - TL) & 255; Ls = 256; }
;             const int hw = 1 << (lane >> 4);
;             const int lo = max(pos - hw, 0), hi = min(pos + hw, Ls);
;             const bf16* base = POOLb + (size_t)(row - pos) * 512 + 8 * lane;
;             float s[8];
; #pragma unroll
;             for (int e = 0; e < 8; ++e) s[e] = 0.f;
;             v4u av[16];
; #pragma unroll
;             for (int k = 0; k < 16; ++k) { const int p = lo + k; const int pc = p < hi ? p : pos; av[k] = *(const v4u*)(base + (size_t)pc * 512); }
	global_load_dwordx4 v[72:75], v188, s[22:23] offset:768
	v_add_u32_e32 v179, 1, v176
	v_add_u32_e32 v180, 2, v176
	v_add_u32_e32 v181, 3, v176
	v_add_u32_e32 v182, 4, v176
	v_cmp_lt_i32_e64 s[30:31], v179, v177
	v_cmp_lt_i32_e64 s[34:35], v180, v177
	v_cmp_lt_i32_e64 s[36:37], v181, v177
	v_cmp_lt_i32_e64 s[38:39], v182, v177
	v_cndmask_b32_e64 v183, v172, v179, s[30:31]
	v_cndmask_b32_e64 v151, 0, 1.0, s[30:31]
	v_lshl_add_u32 v187, v183, 10, v173
	global_load_dwordx4 v[76:79], v187, s[22:23] offset:768
	v_cndmask_b32_e64 v184, v172, v180, s[34:35]
	v_cndmask_b32_e64 v152, 0, 1.0, s[34:35]
	v_lshl_add_u32 v188, v184, 10, v173
	global_load_dwordx4 v[80:83], v188, s[22:23] offset:768
	v_cndmask_b32_e64 v185, v172, v181, s[36:37]
	v_cndmask_b32_e64 v153, 0, 1.0, s[36:37]
	v_lshl_add_u32 v189, v185, 10, v173
	global_load_dwordx4 v[84:87], v189, s[22:23] offset:768
	v_cndmask_b32_e64 v186, v172, v182, s[38:39]
	v_cndmask_b32_e64 v154, 0, 1.0, s[38:39]
	v_lshl_add_u32 v190, v186, 10, v173
	global_load_dwordx4 v[88:91], v190, s[22:23] offset:768
	v_add_u32_e32 v179, 5, v176
	v_add_u32_e32 v180, 6, v176
	v_add_u32_e32 v181, 7, v176
	v_add_u32_e32 v182, 8, v176
	v_cmp_lt_i32_e64 s[30:31], v179, v177
	v_cmp_lt_i32_e64 s[34:35], v180, v177
	v_cmp_lt_i32_e64 s[36:37], v181, v177
	v_cmp_lt_i32_e64 s[38:39], v182, v177
	v_cndmask_b32_e64 v183, v172, v179, s[30:31]
	v_cndmask_b32_e64 v155, 0, 1.0, s[30:31]
	v_lshl_add_u32 v187, v183, 10, v173
	global_load_dwordx4 v[92:95], v187, s[22:23] offset:768
	v_cndmask_b32_e64 v184, v172, v180, s[34:35]
	v_cndmask_b32_e64 v156, 0, 1.0, s[34:35]
	v_lshl_add_u32 v188, v184, 10, v173
	global_load_dwordx4 v[96:99], v188, s[22:23] offset:768
	v_cndmask_b32_e64 v185, v172, v181, s[36:37]
	v_cndmask_b32_e64 v157, 0, 1.0, s[36:37]
	v_lshl_add_u32 v189, v185, 10, v173
	global_load_dwordx4 v[100:103], v189, s[22:23] offset:768
	v_cndmask_b32_e64 v186, v172, v182, s[38:39]
	v_cndmask_b32_e64 v158, 0, 1.0, s[38:39]
	v_lshl_add_u32 v190, v186, 10, v173
	global_load_dwordx4 v[104:107], v190, s[22:23] offset:768
	v_add_u32_e32 v179, 9, v176
	v_add_u32_e32 v180, 10, v176
	v_add_u32_e32 v181, 11, v176
	v_add_u32_e32 v182, 12, v176
	v_cmp_lt_i32_e64 s[30:31], v179, v177
	v_cmp_lt_i32_e64 s[34:35], v180, v177
	v_cmp_lt_i32_e64 s[36:37], v181, v177
	v_cmp_lt_i32_e64 s[38:39], v182, v177
	v_cndmask_b32_e64 v183, v172, v179, s[30:31]
	v_cndmask_b32_e64 v159, 0, 1.0, s[30:31]
	v_lshl_add_u32 v187, v183, 10, v173
	global_load_dwordx4 v[108:111], v187, s[22:23] offset:768
	v_cndmask_b32_e64 v184, v172, v180, s[34:35]
	v_cndmask_b32_e64 v160, 0, 1.0, s[34:35]
	v_lshl_add_u32 v188, v184, 10, v173
	global_load_dwordx4 v[112:115], v188, s[22:23] offset:768
	v_cndmask_b32_e64 v185, v172, v181, s[36:37]
	v_cndmask_b32_e64 v161, 0, 1.0, s[36:37]
	v_lshl_add_u32 v189, v185, 10, v173
	global_load_dwordx4 v[116:119], v189, s[22:23] offset:768
	v_cndmask_b32_e64 v186, v172, v182, s[38:39]
	v_cndmask_b32_e64 v162, 0, 1.0, s[38:39]
	v_lshl_add_u32 v190, v186, 10, v173
	global_load_dwordx4 v[120:123], v190, s[22:23] offset:768
	v_add_u32_e32 v179, 13, v176
	v_add_u32_e32 v180, 14, v176
	v_add_u32_e32 v181, 15, v176
	v_cmp_lt_i32_e64 s[30:31], v179, v177
	v_cmp_lt_i32_e64 s[34:35], v180, v177
	v_cmp_lt_i32_e64 s[36:37], v181, v177
	v_cndmask_b32_e64 v183, v172, v179, s[30:31]
	v_cndmask_b32_e64 v163, 0, 1.0, s[30:31]
	v_lshl_add_u32 v187, v183, 10, v173
	global_load_dwordx4 v[124:127], v187, s[22:23] offset:768
	v_cndmask_b32_e64 v184, v172, v180, s[34:35]
	v_cndmask_b32_e64 v164, 0, 1.0, s[34:35]
	v_lshl_add_u32 v188, v184, 10, v173
	global_load_dwordx4 v[128:131], v188, s[22:23] offset:768
	v_cndmask_b32_e64 v185, v172, v181, s[36:37]
	v_cndmask_b32_e64 v165, 0, 1.0, s[36:37]
	v_lshl_add_u32 v189, v185, 10, v173
	global_load_dwordx4 v[132:135], v189, s[22:23] offset:768
	v_cvt_f32_i32_e32 v178, v178
	v_div_scale_f32 v212, s[40:41], v178, v178, 1.0
	v_div_scale_f32 v215, vcc, 1.0, v178, 1.0
	v_rcp_f32_e32 v213, v212
	s_nop 0
	v_fma_f32 v214, -v212, v213, 1.0
	v_fmac_f32_e32 v213, v214, v213
	v_mul_f32_e32 v216, v215, v213
	v_fma_f32 v217, -v212, v216, v215
	v_fmac_f32_e32 v216, v217, v213
	v_fma_f32 v218, -v212, v216, v215
	v_div_fmas_f32 v219, v218, v213, v216
	v_div_fixup_f32 v169, v219, v178, 1.0
	s_cmp_eq_u32 s29, 1
	s_cbranch_scc1 .Lc1_loop_L0

; __device__ __forceinline__ float bflo(unsigned u) { return __uint_as_float(u << 16); }
; __device__ __forceinline__ float bfhi(unsigned u) { return __uint_as_float(u & 0xffff0000u); }
; template <int l> __device__ __forceinline__ void layer_body(LAS unsigned char* lds, const int wave_s) {
;     ...
;         for (int row = gw; row < rows_post; row += NGW) {
;             int pos, Ls; if (row < TL) { pos = row & 63; Ls = 64; } else { pos = (row - TL) & 255; Ls = 256; }
;             const int hw = 1 << (lane >> 4);
;             const int lo = max(pos - hw, 0), hi = min(pos + hw, Ls);
;             const bf16* base = POOLb + (size_t)(row - pos) * 512 + 8 * lane;
;             float s[8];
; #pragma unroll
;             for (int e = 0; e < 8; ++e) s[e] = 0.f;
;             v4u av[16];
; #pragma unroll
;             for (int k = 0; k < 16; ++k) { const int p = lo + k; const int pc = p < hi ? p : pos; av[k] = *(const v4u*)(base + (size_t)pc * 512); }
; #pragma unroll
;             for (int k = 0; k < 16; ++k) { const float vm = (lo + k < hi) ? 1.f : 0.f; const v4u a = av[k];
;                 s[0] += vm * bflo(a.x); s[1] += vm * bfhi(a.x); s[2] += vm * bflo(a.y); s[3] += vm * bfhi(a.y); s[4] += vm * bflo(a.z); s[5] += vm * bfhi(a.z); s[6] += vm * bflo(a.w); s[7] += vm * bfhi(a.w); }
;             const v4u me = *(const v4u*)(base + (size_t)pos * 512); const float inv = 1.0f / (float)(hi - lo);
.LBB0_1197:
	v_readlane_b32 s2, v255, 4
	v_readlane_b32 s3, v255, 5
	s_mov_b64 s[0:1], s[84:85]
	s_andn2_b64 vcc, exec, s[2:3]
	s_waitcnt lgkmcnt(0)
	v_cndmask_b32_e64 v0, 0, 1, s[2:3]
	v_cmp_ne_u32_e64 s[4:5], 1, v0
	s_barrier
	s_nop 0
	v_writelane_b32 v255, s4, 2
	v_mbcnt_lo_u32_b32 v0, -1, 0
	v_mbcnt_hi_u32_b32 v0, -1, v0
	s_nop 1
	v_writelane_b32 v255, s5, 3
	s_cbranch_vccnz .LBB0_1200
	s_load_dwordx2 s[2:3], s[84:85], 0xd0
	v_lshrrev_b32_e32 v170, 4, v0
	v_and_b32_e32 v171, 15, v0
	v_lshlrev_b32_e32 v171, 4, v171
	v_lshl_add_u32 v174, v170, 10, v171
	s_mov_b32 s4, s80
	s_waitcnt lgkmcnt(0)
	s_add_u32 s22, s2, 0x11f00000
	s_addc_u32 s23, s3, 0
	s_add_u32 s24, s2, 0x1eb00000
	s_addc_u32 s25, s3, 0
	s_lshl_b32 s6, s4, 2
	s_cmp_lt_i32 s6, 0x10000
	s_cselect_b32 s26, 63, 0xff
	s_cselect_b32 s19, 64, 0x100
	s_and_b32 s18, s6, s26
	s_sub_i32 s27, s6, s18
	s_lshl_b32 s27, s27, 10
	v_add_u32_e32 v172, s18, v170
	v_add_u32_e32 v173, s27, v171
	v_subrev_u32_e32 v176, 1, v172
	v_add_u32_e32 v177, 1, v172
	v_max_i32_e32 v176, 0, v176
	v_min_i32_e32 v177, s19, v177
	v_lshl_add_u32 v187, v172, 10, v173
	v_sub_u32_e32 v178, v177, v176
	global_load_dwordx4 v[0:3], v187, s[22:23]
	v_lshl_add_u32 v188, v176, 10, v173
	v_mov_b32_e32 v136, 1.0
	global_load_dwordx4 v[4:7], v188, s[22:23]
	v_add_u32_e32 v179, 1, v176
	v_cmp_lt_i32_e64 s[30:31], v179, v177
	s_nop 1
	v_cndmask_b32_e64 v183, v172, v179, s[30:31]
	v_cndmask_b32_e64 v137, 0, 1.0, s[30:31]
	v_lshl_add_u32 v187, v183, 10, v173
	global_load_dwordx4 v[8:11], v187, s[22:23]
	v_cvt_f32_i32_e32 v178, v178
	v_div_scale_f32 v212, s[40:41], v178, v178, 1.0
	v_div_scale_f32 v215, vcc, 1.0, v178, 1.0
	v_rcp_f32_e32 v213, v212
	s_nop 0
	v_fma_f32 v214, -v212, v213, 1.0
	v_fmac_f32_e32 v213, v214, v213
	v_mul_f32_e32 v216, v215, v213
	v_fma_f32 v217, -v212, v216, v215
	v_fmac_f32_e32 v216, v217, v213
	v_fma_f32 v218, -v212, v216, v215
	v_div_fmas_f32 v219, v218, v213, v216
	v_div_fixup_f32 v166, v219, v178, 1.0
	v_subrev_u32_e32 v176, 2, v172
	v_add_u32_e32 v177, 2, v172
	v_max_i32_e32 v176, 0, v176
	v_min_i32_e32 v177, s19, v177
	v_lshl_add_u32 v187, v172, 10, v173
	v_sub_u32_e32 v178, v177, v176
	global_load_dwordx4 v[12:15], v187, s[22:23] offset:256
	v_lshl_add_u32 v188, v176, 10, v173
	v_mov_b32_e32 v138, 1.0
	global_load_dwordx4 v[16:19], v188, s[22:23] offset:256
	v_add_u32_e32 v179, 1, v176
	v_add_u32_e32 v180, 2, v176
	v_add_u32_e32 v181, 3, v176
	v_cmp_lt_i32_e64 s[30:31], v179, v177
	v_cmp_lt_i32_e64 s[34:35], v180, v177
	v_cmp_lt_i32_e64 s[36:37], v181, v177
	v_cndmask_b32_e64 v183, v172, v179, s[30:31]
	v_cndmask_b32_e64 v139, 0, 1.0, s[30:31]
	v_lshl_add_u32 v187, v183, 10, v173
	global_load_dwordx4 v[20:23], v187, s[22:23] offset:256
	v_cndmask_b32_e64 v184, v172, v180, s[34:35]
	v_cndmask_b32_e64 v140, 0, 1.0, s[34:35]
	v_lshl_add_u32 v188, v184, 10, v173
	global_load_dwordx4 v[24:27], v188, s[22:23] offset:256
	v_cndmask_b32_e64 v185, v172, v181, s[36:37]
	v_cndmask_b32_e64 v141, 0, 1.0, s[36:37]
	v_lshl_add_u32 v189, v185, 10, v173
	global_load_dwordx4 v[28:31], v189, s[22:23] offset:256
	v_cvt_f32_i32_e32 v178, v178
	v_div_scale_f32 v212, s[40:41], v178, v178, 1.0
	v_div_scale_f32 v215, vcc, 1.0, v178, 1.0
	v_rcp_f32_e32 v213, v212
	s_nop 0
	v_fma_f32 v214, -v212, v213, 1.0
	v_fmac_f32_e32 v213, v214, v213
	v_mul_f32_e32 v216, v215, v213
	v_fma_f32 v217, -v212, v216, v215
	v_fmac_f32_e32 v216, v217, v213
	v_fma_f32 v218, -v212, v216, v215
	v_div_fmas_f32 v219, v218, v213, v216
	v_div_fixup_f32 v167, v219, v178, 1.0
	v_subrev_u32_e32 v176, 4, v172
	v_add_u32_e32 v177, 4, v172
	v_max_i32_e32 v176, 0, v176
	v_min_i32_e32 v177, s19, v177
	v_lshl_add_u32 v187, v172, 10, v173
	v_sub_u32_e32 v178, v177, v176
	global_load_dwordx4 v[32:35], v187, s[22:23] offset:512
	v_lshl_add_u32 v188, v176, 10, v173
	v_mov_b32_e32 v142, 1.0
	global_load_dwordx4 v[36:39], v188, s[22:23] offset:512
	v_add_u32_e32 v179, 1, v176
	v_add_u32_e32 v180, 2, v176
	v_add_u32_e32 v181, 3, v176
	v_add_u32_e32 v182, 4, v176
	v_cmp_lt_i32_e64 s[30:31], v179, v177
	v_cmp_lt_i32_e64 s[34:35], v180, v177
	v_cmp_lt_i32_e64 s[36:37], v181, v177
	v_cmp_lt_i32_e64 s[38:39], v182, v177
	v_cndmask_b32_e64 v183, v172, v179, s[30:31]
	v_cndmask_b32_e64 v143, 0, 1.0, s[30:31]
	v_lshl_add_u32 v187, v183, 10, v173
	global_load_dwordx4 v[40:43], v187, s[22:23] offset:512
	v_cndmask_b32_e64 v184, v172, v180, s[34:35]
	v_cndmask_b32_e64 v144, 0, 1.0, s[34:35]
	v_lshl_add_u32 v188, v184, 10, v173
	global_load_dwordx4 v[44:47], v188, s[22:23] offset:512
	v_cndmask_b32_e64 v185, v172, v181, s[36:37]
	v_cndmask_b32_e64 v145, 0, 1.0, s[36:37]
	v_lshl_add_u32 v189, v185, 10, v173
	global_load_dwordx4 v[48:51], v189, s[22:23] offset:512
	v_cndmask_b32_e64 v186, v172, v182, s[38:39]
	v_cndmask_b32_e64 v146, 0, 1.0, s[38:39]
	v_lshl_add_u32 v190, v186, 10, v173
	global_load_dwordx4 v[52:55], v190, s[22:23] offset:512
	v_add_u32_e32 v179, 5, v176
	v_add_u32_e32 v180, 6, v176
	v_add_u32_e32 v181, 7, v176
	v_cmp_lt_i32_e64 s[30:31], v179, v177
	v_cmp_lt_i32_e64 s[34:35], v180, v177
	v_cmp_lt_i32_e64 s[36:37], v181, v177
	v_cndmask_b32_e64 v183, v172, v179, s[30:31]
	v_cndmask_b32_e64 v147, 0, 1.0, s[30:31]
	v_lshl_add_u32 v187, v183, 10, v173
	global_load_dwordx4 v[56:59], v187, s[22:23] offset:512
	v_cndmask_b32_e64 v184, v172, v180, s[34:35]
; __device__ __forceinline__ float bflo(unsigned u) { return __uint_as_float(u << 16); }
; __device__ __forceinline__ float bfhi(unsigned u) { return __uint_as_float(u & 0xffff0000u); }
; template <int l> __device__ __forceinline__ void layer_body(LAS unsigned char* lds, const int wave_s) {
;     ...
;         for (int row = gw; row < rows_post; row += NGW) {
;             int pos, Ls; if (row < TL) { pos = row & 63; Ls = 64; } else { pos = (row - TL) & 255; Ls = 256; }
;             const int hw = 1 << (lane >> 4);
;             const int lo = max(pos - hw, 0), hi = min(pos + hw, Ls);
;             const bf16* base = POOLb + (size_t)(row - pos) * 512 + 8 * lane;
;             float s[8];
; #pragma unroll
;             for (int e = 0; e < 8; ++e) s[e] = 0.f;
;             v4u av[16];
; #pragma unroll
;             for (int k = 0; k < 16; ++k) { const int p = lo + k; const int pc = p < hi ? p : pos; av[k] = *(const v4u*)(base + (size_t)pc * 512); }
; #pragma unroll
;             for (int k = 0; k < 16; ++k) { const float vm = (lo + k < hi) ? 1.f : 0.f; const v4u a = av[k];
;                 s[0] += vm * bflo(a.x); s[1] += vm * bfhi(a.x); s[2] += vm * bflo(a.y); s[3] += vm * bfhi(a.y); s[4] += vm * bflo(a.z); s[5] += vm * bfhi(a.z); s[6] += vm * bflo(a.w); s[7] += vm * bfhi(a.w); }
;             const v4u me = *(const v4u*)(base + (size_t)pos * 512); const float inv = 1.0f / (float)(hi - lo);
	v_cndmask_b32_e64 v148, 0, 1.0, s[34:35]
	v_lshl_add_u32 v188, v184, 10, v173
	global_load_dwordx4 v[60:63], v188, s[22:23] offset:512
	v_cndmask_b32_e64 v185, v172, v181, s[36:37]
	v_cndmask_b32_e64 v149, 0, 1.0, s[36:37]
	v_lshl_add_u32 v189, v185, 10, v173
	global_load_dwordx4 v[64:67], v189, s[22:23] offset:512
	v_cvt_f32_i32_e32 v178, v178
	v_div_scale_f32 v212, s[40:41], v178, v178, 1.0
	v_div_scale_f32 v215, vcc, 1.0, v178, 1.0
	v_rcp_f32_e32 v213, v212
	s_nop 0
	v_fma_f32 v214, -v212, v213, 1.0
	v_fmac_f32_e32 v213, v214, v213
	v_mul_f32_e32 v216, v215, v213
	v_fma_f32 v217, -v212, v216, v215
	v_fmac_f32_e32 v216, v217, v213
	v_fma_f32 v218, -v212, v216, v215
	v_div_fmas_f32 v219, v218, v213, v216
	v_div_fixup_f32 v168, v219, v178, 1.0
	v_subrev_u32_e32 v176, 8, v172
	v_add_u32_e32 v177, 8, v172
	v_max_i32_e32 v176, 0, v176
	v_min_i32_e32 v177, s19, v177
	v_lshl_add_u32 v187, v172, 10, v173
	v_sub_u32_e32 v178, v177, v176
	global_load_dwordx4 v[68:71], v187, s[22:23] offset:768
	v_lshl_add_u32 v188, v176, 10, v173
	v_mov_b32_e32 v150, 1.0
	global_load_dwordx4 v[72:75], v188, s[22:23] offset:768
	v_add_u32_e32 v179, 1, v176
	v_add_u32_e32 v180, 2, v176
	v_add_u32_e32 v181, 3, v176
	v_add_u32_e32 v182, 4, v176
	v_cmp_lt_i32_e64 s[30:31], v179, v177
	v_cmp_lt_i32_e64 s[34:35], v180, v177
	v_cmp_lt_i32_e64 s[36:37], v181, v177
	v_cmp_lt_i32_e64 s[38:39], v182, v177
	v_cndmask_b32_e64 v183, v172, v179, s[30:31]
	v_cndmask_b32_e64 v151, 0, 1.0, s[30:31]
	v_lshl_add_u32 v187, v183, 10, v173
	global_load_dwordx4 v[76:79], v187, s[22:23] offset:768
	v_cndmask_b32_e64 v184, v172, v180, s[34:35]
	v_cndmask_b32_e64 v152, 0, 1.0, s[34:35]
	v_lshl_add_u32 v188, v184, 10, v173
	global_load_dwordx4 v[80:83], v188, s[22:23] offset:768
	v_cndmask_b32_e64 v185, v172, v181, s[36:37]
	v_cndmask_b32_e64 v153, 0, 1.0, s[36:37]
	v_lshl_add_u32 v189, v185, 10, v173
	global_load_dwordx4 v[84:87], v189, s[22:23] offset:768
	v_cndmask_b32_e64 v186, v172, v182, s[38:39]
	v_cndmask_b32_e64 v154, 0, 1.0, s[38:39]
	v_lshl_add_u32 v190, v186, 10, v173
	global_load_dwordx4 v[88:91], v190, s[22:23] offset:768
	v_add_u32_e32 v179, 5, v176
	v_add_u32_e32 v180, 6, v176
	v_add_u32_e32 v181, 7, v176
	v_add_u32_e32 v182, 8, v176
	v_cmp_lt_i32_e64 s[30:31], v179, v177
	v_cmp_lt_i32_e64 s[34:35], v180, v177
	v_cmp_lt_i32_e64 s[36:37], v181, v177
	v_cmp_lt_i32_e64 s[38:39], v182, v177
	v_cndmask_b32_e64 v183, v172, v179, s[30:31]
	v_cndmask_b32_e64 v155, 0, 1.0, s[30:31]
	v_lshl_add_u32 v187, v183, 10, v173
	global_load_dwordx4 v[92:95], v187, s[22:23] offset:768
	v_cndmask_b32_e64 v184, v172, v180, s[34:35]
	v_cndmask_b32_e64 v156, 0, 1.0, s[34:35]
	v_lshl_add_u32 v188, v184, 10, v173
	global_load_dwordx4 v[96:99], v188, s[22:23] offset:768
	v_cndmask_b32_e64 v185, v172, v181, s[36:37]
	v_cndmask_b32_e64 v157, 0, 1.0, s[36:37]
	v_lshl_add_u32 v189, v185, 10, v173
	global_load_dwordx4 v[100:103], v189, s[22:23] offset:768
	v_cndmask_b32_e64 v186, v172, v182, s[38:39]
	v_cndmask_b32_e64 v158, 0, 1.0, s[38:39]
	v_lshl_add_u32 v190, v186, 10, v173
	global_load_dwordx4 v[104:107], v190, s[22:23] offset:768
	v_add_u32_e32 v179, 9, v176
	v_add_u32_e32 v180, 10, v176
	v_add_u32_e32 v181, 11, v176
	v_add_u32_e32 v182, 12, v176
	v_cmp_lt_i32_e64 s[30:31], v179, v177
	v_cmp_lt_i32_e64 s[34:35], v180, v177
	v_cmp_lt_i32_e64 s[36:37], v181, v177
	v_cmp_lt_i32_e64 s[38:39], v182, v177
	v_cndmask_b32_e64 v183, v172, v179, s[30:31]
	v_cndmask_b32_e64 v159, 0, 1.0, s[30:31]
	v_lshl_add_u32 v187, v183, 10, v173
	global_load_dwordx4 v[108:111], v187, s[22:23] offset:768
	v_cndmask_b32_e64 v184, v172, v180, s[34:35]
	v_cndmask_b32_e64 v160, 0, 1.0, s[34:35]
	v_lshl_add_u32 v188, v184, 10, v173
	global_load_dwordx4 v[112:115], v188, s[22:23] offset:768
	v_cndmask_b32_e64 v185, v172, v181, s[36:37]
	v_cndmask_b32_e64 v161, 0, 1.0, s[36:37]
	v_lshl_add_u32 v189, v185, 10, v173
	global_load_dwordx4 v[116:119], v189, s[22:23] offset:768
	v_cndmask_b32_e64 v186, v172, v182, s[38:39]
	v_cndmask_b32_e64 v162, 0, 1.0, s[38:39]
	v_lshl_add_u32 v190, v186, 10, v173
	global_load_dwordx4 v[120:123], v190, s[22:23] offset:768
	v_add_u32_e32 v179, 13, v176
	v_add_u32_e32 v180, 14, v176
	v_add_u32_e32 v181, 15, v176
	v_cmp_lt_i32_e64 s[30:31], v179, v177
	v_cmp_lt_i32_e64 s[34:35], v180, v177
	v_cmp_lt_i32_e64 s[36:37], v181, v177
	v_cndmask_b32_e64 v183, v172, v179, s[30:31]
	v_cndmask_b32_e64 v163, 0, 1.0, s[30:31]
	v_lshl_add_u32 v187, v183, 10, v173
	global_load_dwordx4 v[124:127], v187, s[22:23] offset:768
	v_cndmask_b32_e64 v184, v172, v180, s[34:35]
	v_cndmask_b32_e64 v164, 0, 1.0, s[34:35]
	v_lshl_add_u32 v188, v184, 10, v173
	global_load_dwordx4 v[128:131], v188, s[22:23] offset:768
	v_cndmask_b32_e64 v185, v172, v181, s[36:37]
	v_cndmask_b32_e64 v165, 0, 1.0, s[36:37]
	v_lshl_add_u32 v189, v185, 10, v173
	global_load_dwordx4 v[132:135], v189, s[22:23] offset:768
	v_cvt_f32_i32_e32 v178, v178
	v_div_scale_f32 v212, s[40:41], v178, v178, 1.0
	v_div_scale_f32 v215, vcc, 1.0, v178, 1.0
	v_rcp_f32_e32 v213, v212
	s_nop 0
	v_fma_f32 v214, -v212, v213, 1.0
	v_fmac_f32_e32 v213, v214, v213
	v_mul_f32_e32 v216, v215, v213
	v_fma_f32 v217, -v212, v216, v215
	v_fmac_f32_e32 v216, v217, v213
	v_fma_f32 v218, -v212, v216, v215
	v_div_fmas_f32 v219, v218, v213, v216
	v_div_fixup_f32 v169, v219, v178, 1.0

; __device__ __forceinline__ float bflo(unsigned u) { return __uint_as_float(u << 16); }
; __device__ __forceinline__ float bfhi(unsigned u) { return __uint_as_float(u & 0xffff0000u); }
; template <int l> __device__ __forceinline__ void layer_body(LAS unsigned char* lds, const int wave_s) {
;     ...
;         for (int row = gw; row < rows_post; row += NGW) {
;             int pos, Ls; if (row < TL) { pos = row & 63; Ls = 64; } else { pos = (row - TL) & 255; Ls = 256; }
;             const int hw = 1 << (lane >> 4);
;             const int lo = max(pos - hw, 0), hi = min(pos + hw, Ls);
;             const bf16* base = POOLb + (size_t)(row - pos) * 512 + 8 * lane;
;             float s[8];
; #pragma unroll
;             for (int e = 0; e < 8; ++e) s[e] = 0.f;
;             v4u av[16];
; #pragma unroll
;             for (int k = 0; k < 16; ++k) { const int p = lo + k; const int pc = p < hi ? p : pos; av[k] = *(const v4u*)(base + (size_t)pc * 512); }
; #pragma unroll
;             for (int k = 0; k < 16; ++k) { const float vm = (lo + k < hi) ? 1.f : 0.f; const v4u a = av[k];
;                 s[0] += vm * bflo(a.x); s[1] += vm * bfhi(a.x); s[2] += vm * bflo(a.y); s[3] += vm * bfhi(a.y); s[4] += vm * bflo(a.z); s[5] += vm * bfhi(a.z); s[6] += vm * bflo(a.w); s[7] += vm * bfhi(a.w); }
;             const v4u me = *(const v4u*)(base + (size_t)pos * 512); const float inv = 1.0f / (float)(hi - lo);
.LBB0_1957:
	v_readlane_b32 s2, v255, 2
	v_readlane_b32 s3, v255, 3
	s_mov_b64 s[0:1], s[84:85]
	s_and_b64 vcc, exec, s[2:3]
	s_waitcnt lgkmcnt(0)
	s_barrier
	v_mbcnt_lo_u32_b32 v0, -1, 0
	v_mbcnt_hi_u32_b32 v0, -1, v0
	s_cbranch_vccnz .LBB0_1960
	s_load_dwordx2 s[2:3], s[84:85], 0xd0
	v_lshrrev_b32_e32 v170, 4, v0
	v_and_b32_e32 v171, 15, v0
	v_lshlrev_b32_e32 v171, 4, v171
	v_lshl_add_u32 v174, v170, 10, v171
	s_mov_b32 s4, s80
	s_waitcnt lgkmcnt(0)
	s_add_u32 s22, s2, 0x11f00000
	s_addc_u32 s23, s3, 0
	s_add_u32 s24, s2, 0x1eb00000
	s_addc_u32 s25, s3, 0
	s_lshl_b32 s6, s4, 2
	s_cmp_lt_i32 s6, 0x10000
	s_cselect_b32 s26, 63, 0xff
	s_cselect_b32 s19, 64, 0x100
	s_and_b32 s18, s6, s26
	s_sub_i32 s27, s6, s18
	s_lshl_b32 s27, s27, 10
	v_add_u32_e32 v172, s18, v170
	v_add_u32_e32 v173, s27, v171
	v_subrev_u32_e32 v176, 1, v172
	v_add_u32_e32 v177, 1, v172
	v_max_i32_e32 v176, 0, v176
	v_min_i32_e32 v177, s19, v177
	v_lshl_add_u32 v187, v172, 10, v173
	v_sub_u32_e32 v178, v177, v176
	global_load_dwordx4 v[0:3], v187, s[22:23]
	v_lshl_add_u32 v188, v176, 10, v173
	v_mov_b32_e32 v136, 1.0
	global_load_dwordx4 v[4:7], v188, s[22:23]
	v_add_u32_e32 v179, 1, v176
	v_cmp_lt_i32_e64 s[30:31], v179, v177
	s_nop 1
	v_cndmask_b32_e64 v183, v172, v179, s[30:31]
	v_cndmask_b32_e64 v137, 0, 1.0, s[30:31]
	v_lshl_add_u32 v187, v183, 10, v173
	global_load_dwordx4 v[8:11], v187, s[22:23]
	v_cvt_f32_i32_e32 v178, v178
	v_div_scale_f32 v212, s[40:41], v178, v178, 1.0
	v_div_scale_f32 v215, vcc, 1.0, v178, 1.0
	v_rcp_f32_e32 v213, v212
	s_nop 0
	v_fma_f32 v214, -v212, v213, 1.0
	v_fmac_f32_e32 v213, v214, v213
	v_mul_f32_e32 v216, v215, v213
	v_fma_f32 v217, -v212, v216, v215
	v_fmac_f32_e32 v216, v217, v213
	v_fma_f32 v218, -v212, v216, v215
	v_div_fmas_f32 v219, v218, v213, v216
	v_div_fixup_f32 v166, v219, v178, 1.0
	v_subrev_u32_e32 v176, 2, v172
	v_add_u32_e32 v177, 2, v172
	v_max_i32_e32 v176, 0, v176
	v_min_i32_e32 v177, s19, v177
	v_lshl_add_u32 v187, v172, 10, v173
	v_sub_u32_e32 v178, v177, v176
	global_load_dwordx4 v[12:15], v187, s[22:23] offset:256
	v_lshl_add_u32 v188, v176, 10, v173
	v_mov_b32_e32 v138, 1.0
	global_load_dwordx4 v[16:19], v188, s[22:23] offset:256
	v_add_u32_e32 v179, 1, v176
	v_add_u32_e32 v180, 2, v176
	v_add_u32_e32 v181, 3, v176
	v_cmp_lt_i32_e64 s[30:31], v179, v177
	v_cmp_lt_i32_e64 s[34:35], v180, v177
	v_cmp_lt_i32_e64 s[36:37], v181, v177
	v_cndmask_b32_e64 v183, v172, v179, s[30:31]
	v_cndmask_b32_e64 v139, 0, 1.0, s[30:31]
	v_lshl_add_u32 v187, v183, 10, v173
	global_load_dwordx4 v[20:23], v187, s[22:23] offset:256
	v_cndmask_b32_e64 v184, v172, v180, s[34:35]
	v_cndmask_b32_e64 v140, 0, 1.0, s[34:35]
	v_lshl_add_u32 v188, v184, 10, v173
	global_load_dwordx4 v[24:27], v188, s[22:23] offset:256
	v_cndmask_b32_e64 v185, v172, v181, s[36:37]
	v_cndmask_b32_e64 v141, 0, 1.0, s[36:37]
	v_lshl_add_u32 v189, v185, 10, v173
	global_load_dwordx4 v[28:31], v189, s[22:23] offset:256
	v_cvt_f32_i32_e32 v178, v178
	v_div_scale_f32 v212, s[40:41], v178, v178, 1.0
	v_div_scale_f32 v215, vcc, 1.0, v178, 1.0
	v_rcp_f32_e32 v213, v212
	s_nop 0
	v_fma_f32 v214, -v212, v213, 1.0
	v_fmac_f32_e32 v213, v214, v213
	v_mul_f32_e32 v216, v215, v213
	v_fma_f32 v217, -v212, v216, v215
	v_fmac_f32_e32 v216, v217, v213
	v_fma_f32 v218, -v212, v216, v215
	v_div_fmas_f32 v219, v218, v213, v216
	v_div_fixup_f32 v167, v219, v178, 1.0
	v_subrev_u32_e32 v176, 4, v172
	v_add_u32_e32 v177, 4, v172
	v_max_i32_e32 v176, 0, v176
	v_min_i32_e32 v177, s19, v177
	v_lshl_add_u32 v187, v172, 10, v173
	v_sub_u32_e32 v178, v177, v176
	global_load_dwordx4 v[32:35], v187, s[22:23] offset:512
	v_lshl_add_u32 v188, v176, 10, v173
	v_mov_b32_e32 v142, 1.0
	global_load_dwordx4 v[36:39], v188, s[22:23] offset:512
	v_add_u32_e32 v179, 1, v176
	v_add_u32_e32 v180, 2, v176
	v_add_u32_e32 v181, 3, v176
	v_add_u32_e32 v182, 4, v176
	v_cmp_lt_i32_e64 s[30:31], v179, v177
	v_cmp_lt_i32_e64 s[34:35], v180, v177
	v_cmp_lt_i32_e64 s[36:37], v181, v177
	v_cmp_lt_i32_e64 s[38:39], v182, v177
	v_cndmask_b32_e64 v183, v172, v179, s[30:31]
	v_cndmask_b32_e64 v143, 0, 1.0, s[30:31]
	v_lshl_add_u32 v187, v183, 10, v173
	global_load_dwordx4 v[40:43], v187, s[22:23] offset:512
	v_cndmask_b32_e64 v184, v172, v180, s[34:35]
	v_cndmask_b32_e64 v144, 0, 1.0, s[34:35]
	v_lshl_add_u32 v188, v184, 10, v173
	global_load_dwordx4 v[44:47], v188, s[22:23] offset:512
	v_cndmask_b32_e64 v185, v172, v181, s[36:37]
	v_cndmask_b32_e64 v145, 0, 1.0, s[36:37]
	v_lshl_add_u32 v189, v185, 10, v173
	global_load_dwordx4 v[48:51], v189, s[22:23] offset:512
	v_cndmask_b32_e64 v186, v172, v182, s[38:39]
	v_cndmask_b32_e64 v146, 0, 1.0, s[38:39]
	v_lshl_add_u32 v190, v186, 10, v173
	global_load_dwordx4 v[52:55], v190, s[22:23] offset:512
	v_add_u32_e32 v179, 5, v176
	v_add_u32_e32 v180, 6, v176
	v_add_u32_e32 v181, 7, v176
	v_cmp_lt_i32_e64 s[30:31], v179, v177
	v_cmp_lt_i32_e64 s[34:35], v180, v177
	v_cmp_lt_i32_e64 s[36:37], v181, v177
	v_cndmask_b32_e64 v183, v172, v179, s[30:31]
	v_cndmask_b32_e64 v147, 0, 1.0, s[30:31]
	v_lshl_add_u32 v187, v183, 10, v173
	global_load_dwordx4 v[56:59], v187, s[22:23] offset:512
	v_cndmask_b32_e64 v184, v172, v180, s[34:35]
	v_cndmask_b32_e64 v148, 0, 1.0, s[34:35]
	v_lshl_add_u32 v188, v184, 10, v173
; __device__ __forceinline__ float bflo(unsigned u) { return __uint_as_float(u << 16); }
; __device__ __forceinline__ float bfhi(unsigned u) { return __uint_as_float(u & 0xffff0000u); }
; template <int l> __device__ __forceinline__ void layer_body(LAS unsigned char* lds, const int wave_s) {
;     ...
;         for (int row = gw; row < rows_post; row += NGW) {
;             int pos, Ls; if (row < TL) { pos = row & 63; Ls = 64; } else { pos = (row - TL) & 255; Ls = 256; }
;             const int hw = 1 << (lane >> 4);
;             const int lo = max(pos - hw, 0), hi = min(pos + hw, Ls);
;             const bf16* base = POOLb + (size_t)(row - pos) * 512 + 8 * lane;
;             float s[8];
; #pragma unroll
;             for (int e = 0; e < 8; ++e) s[e] = 0.f;
;             v4u av[16];
; #pragma unroll
;             for (int k = 0; k < 16; ++k) { const int p = lo + k; const int pc = p < hi ? p : pos; av[k] = *(const v4u*)(base + (size_t)pc * 512); }
; #pragma unroll
;             for (int k = 0; k < 16; ++k) { const float vm = (lo + k < hi) ? 1.f : 0.f; const v4u a = av[k];
;                 s[0] += vm * bflo(a.x); s[1] += vm * bfhi(a.x); s[2] += vm * bflo(a.y); s[3] += vm * bfhi(a.y); s[4] += vm * bflo(a.z); s[5] += vm * bfhi(a.z); s[6] += vm * bflo(a.w); s[7] += vm * bfhi(a.w); }
;             const v4u me = *(const v4u*)(base + (size_t)pos * 512); const float inv = 1.0f / (float)(hi - lo);
	global_load_dwordx4 v[60:63], v188, s[22:23] offset:512
	v_cndmask_b32_e64 v185, v172, v181, s[36:37]
	v_cndmask_b32_e64 v149, 0, 1.0, s[36:37]
	v_lshl_add_u32 v189, v185, 10, v173
	global_load_dwordx4 v[64:67], v189, s[22:23] offset:512
	v_cvt_f32_i32_e32 v178, v178
	v_div_scale_f32 v212, s[40:41], v178, v178, 1.0
	v_div_scale_f32 v215, vcc, 1.0, v178, 1.0
	v_rcp_f32_e32 v213, v212
	s_nop 0
	v_fma_f32 v214, -v212, v213, 1.0
	v_fmac_f32_e32 v213, v214, v213
	v_mul_f32_e32 v216, v215, v213
	v_fma_f32 v217, -v212, v216, v215
	v_fmac_f32_e32 v216, v217, v213
	v_fma_f32 v218, -v212, v216, v215
	v_div_fmas_f32 v219, v218, v213, v216
	v_div_fixup_f32 v168, v219, v178, 1.0
	v_subrev_u32_e32 v176, 8, v172
	v_add_u32_e32 v177, 8, v172
	v_max_i32_e32 v176, 0, v176
	v_min_i32_e32 v177, s19, v177
	v_lshl_add_u32 v187, v172, 10, v173
	v_sub_u32_e32 v178, v177, v176
	global_load_dwordx4 v[68:71], v187, s[22:23] offset:768
	v_lshl_add_u32 v188, v176, 10, v173
	v_mov_b32_e32 v150, 1.0
	global_load_dwordx4 v[72:75], v188, s[22:23] offset:768
	v_add_u32_e32 v179, 1, v176
	v_add_u32_e32 v180, 2, v176
	v_add_u32_e32 v181, 3, v176
	v_add_u32_e32 v182, 4, v176
	v_cmp_lt_i32_e64 s[30:31], v179, v177
	v_cmp_lt_i32_e64 s[34:35], v180, v177
	v_cmp_lt_i32_e64 s[36:37], v181, v177
	v_cmp_lt_i32_e64 s[38:39], v182, v177
	v_cndmask_b32_e64 v183, v172, v179, s[30:31]
	v_cndmask_b32_e64 v151, 0, 1.0, s[30:31]
	v_lshl_add_u32 v187, v183, 10, v173
	global_load_dwordx4 v[76:79], v187, s[22:23] offset:768
	v_cndmask_b32_e64 v184, v172, v180, s[34:35]
	v_cndmask_b32_e64 v152, 0, 1.0, s[34:35]
	v_lshl_add_u32 v188, v184, 10, v173
	global_load_dwordx4 v[80:83], v188, s[22:23] offset:768
	v_cndmask_b32_e64 v185, v172, v181, s[36:37]
	v_cndmask_b32_e64 v153, 0, 1.0, s[36:37]
	v_lshl_add_u32 v189, v185, 10, v173
	global_load_dwordx4 v[84:87], v189, s[22:23] offset:768
	v_cndmask_b32_e64 v186, v172, v182, s[38:39]
	v_cndmask_b32_e64 v154, 0, 1.0, s[38:39]
	v_lshl_add_u32 v190, v186, 10, v173
	global_load_dwordx4 v[88:91], v190, s[22:23] offset:768
	v_add_u32_e32 v179, 5, v176
	v_add_u32_e32 v180, 6, v176
	v_add_u32_e32 v181, 7, v176
	v_add_u32_e32 v182, 8, v176
	v_cmp_lt_i32_e64 s[30:31], v179, v177
	v_cmp_lt_i32_e64 s[34:35], v180, v177
	v_cmp_lt_i32_e64 s[36:37], v181, v177
	v_cmp_lt_i32_e64 s[38:39], v182, v177
	v_cndmask_b32_e64 v183, v172, v179, s[30:31]
	v_cndmask_b32_e64 v155, 0, 1.0, s[30:31]
	v_lshl_add_u32 v187, v183, 10, v173
	global_load_dwordx4 v[92:95], v187, s[22:23] offset:768
	v_cndmask_b32_e64 v184, v172, v180, s[34:35]
	v_cndmask_b32_e64 v156, 0, 1.0, s[34:35]
	v_lshl_add_u32 v188, v184, 10, v173
	global_load_dwordx4 v[96:99], v188, s[22:23] offset:768
	v_cndmask_b32_e64 v185, v172, v181, s[36:37]
	v_cndmask_b32_e64 v157, 0, 1.0, s[36:37]
	v_lshl_add_u32 v189, v185, 10, v173
	global_load_dwordx4 v[100:103], v189, s[22:23] offset:768
	v_cndmask_b32_e64 v186, v172, v182, s[38:39]
	v_cndmask_b32_e64 v158, 0, 1.0, s[38:39]
	v_lshl_add_u32 v190, v186, 10, v173
	global_load_dwordx4 v[104:107], v190, s[22:23] offset:768
	v_add_u32_e32 v179, 9, v176
	v_add_u32_e32 v180, 10, v176
	v_add_u32_e32 v181, 11, v176
	v_add_u32_e32 v182, 12, v176
	v_cmp_lt_i32_e64 s[30:31], v179, v177
	v_cmp_lt_i32_e64 s[34:35], v180, v177
	v_cmp_lt_i32_e64 s[36:37], v181, v177
	v_cmp_lt_i32_e64 s[38:39], v182, v177
	v_cndmask_b32_e64 v183, v172, v179, s[30:31]
	v_cndmask_b32_e64 v159, 0, 1.0, s[30:31]
	v_lshl_add_u32 v187, v183, 10, v173
	global_load_dwordx4 v[108:111], v187, s[22:23] offset:768
	v_cndmask_b32_e64 v184, v172, v180, s[34:35]
	v_cndmask_b32_e64 v160, 0, 1.0, s[34:35]
	v_lshl_add_u32 v188, v184, 10, v173
	global_load_dwordx4 v[112:115], v188, s[22:23] offset:768
	v_cndmask_b32_e64 v185, v172, v181, s[36:37]
	v_cndmask_b32_e64 v161, 0, 1.0, s[36:37]
	v_lshl_add_u32 v189, v185, 10, v173
	global_load_dwordx4 v[116:119], v189, s[22:23] offset:768
	v_cndmask_b32_e64 v186, v172, v182, s[38:39]
	v_cndmask_b32_e64 v162, 0, 1.0, s[38:39]
	v_lshl_add_u32 v190, v186, 10, v173
	global_load_dwordx4 v[120:123], v190, s[22:23] offset:768
	v_add_u32_e32 v179, 13, v176
	v_add_u32_e32 v180, 14, v176
	v_add_u32_e32 v181, 15, v176
	v_cmp_lt_i32_e64 s[30:31], v179, v177
	v_cmp_lt_i32_e64 s[34:35], v180, v177
	v_cmp_lt_i32_e64 s[36:37], v181, v177
	v_cndmask_b32_e64 v183, v172, v179, s[30:31]
	v_cndmask_b32_e64 v163, 0, 1.0, s[30:31]
	v_lshl_add_u32 v187, v183, 10, v173
	global_load_dwordx4 v[124:127], v187, s[22:23] offset:768
	v_cndmask_b32_e64 v184, v172, v180, s[34:35]
	v_cndmask_b32_e64 v164, 0, 1.0, s[34:35]
	v_lshl_add_u32 v188, v184, 10, v173
	global_load_dwordx4 v[128:131], v188, s[22:23] offset:768
	v_cndmask_b32_e64 v185, v172, v181, s[36:37]
	v_cndmask_b32_e64 v165, 0, 1.0, s[36:37]
	v_lshl_add_u32 v189, v185, 10, v173
	global_load_dwordx4 v[132:135], v189, s[22:23] offset:768
	v_cvt_f32_i32_e32 v178, v178
	v_div_scale_f32 v212, s[40:41], v178, v178, 1.0
	v_div_scale_f32 v215, vcc, 1.0, v178, 1.0
	v_rcp_f32_e32 v213, v212
	s_nop 0
	v_fma_f32 v214, -v212, v213, 1.0
	v_fmac_f32_e32 v213, v214, v213
	v_mul_f32_e32 v216, v215, v213
	v_fma_f32 v217, -v212, v216, v215
	v_fmac_f32_e32 v216, v217, v213
	v_fma_f32 v218, -v212, v216, v215
	v_div_fmas_f32 v219, v218, v213, v216
	v_div_fixup_f32 v169, v219, v178, 1.0

; __device__ __forceinline__ float bflo(unsigned u) { return __uint_as_float(u << 16); }
; __device__ __forceinline__ float bfhi(unsigned u) { return __uint_as_float(u & 0xffff0000u); }
; template <int l> __device__ __forceinline__ void layer_body(LAS unsigned char* lds, const int wave_s) {
;     ...
;         for (int row = gw; row < rows_post; row += NGW) {
;             int pos, Ls; if (row < TL) { pos = row & 63; Ls = 64; } else { pos = (row - TL) & 255; Ls = 256; }
;             const int hw = 1 << (lane >> 4);
;             const int lo = max(pos - hw, 0), hi = min(pos + hw, Ls);
;             const bf16* base = POOLb + (size_t)(row - pos) * 512 + 8 * lane;
;             float s[8];
; #pragma unroll
;             for (int e = 0; e < 8; ++e) s[e] = 0.f;
;             v4u av[16];
; #pragma unroll
;             for (int k = 0; k < 16; ++k) { const int p = lo + k; const int pc = p < hi ? p : pos; av[k] = *(const v4u*)(base + (size_t)pc * 512); }
; #pragma unroll
;             for (int k = 0; k < 16; ++k) { const float vm = (lo + k < hi) ? 1.f : 0.f; const v4u a = av[k];
;                 s[0] += vm * bflo(a.x); s[1] += vm * bfhi(a.x); s[2] += vm * bflo(a.y); s[3] += vm * bfhi(a.y); s[4] += vm * bflo(a.z); s[5] += vm * bfhi(a.z); s[6] += vm * bflo(a.w); s[7] += vm * bfhi(a.w); }
;             const v4u me = *(const v4u*)(base + (size_t)pos * 512); const float inv = 1.0f / (float)(hi - lo);
.LBB0_2709:
	s_mov_b64 s[0:1], s[84:85]
	s_cmp_gt_i32 s80, 0xffff
	s_waitcnt lgkmcnt(0)
	s_barrier
	v_mbcnt_lo_u32_b32 v0, -1, 0
	v_mbcnt_hi_u32_b32 v0, -1, v0
	s_cbranch_scc1 .LBB0_2712
	s_load_dwordx2 s[2:3], s[84:85], 0xd0
	v_lshrrev_b32_e32 v170, 4, v0
	v_and_b32_e32 v171, 15, v0
	v_lshlrev_b32_e32 v171, 4, v171
	v_lshl_add_u32 v174, v170, 10, v171
	s_mov_b32 s4, s80
	s_waitcnt lgkmcnt(0)
	s_add_u32 s22, s2, 0x11f00000
	s_addc_u32 s23, s3, 0
	s_add_u32 s24, s2, 0x1eb00000
	s_addc_u32 s25, s3, 0
	s_lshl_b32 s6, s4, 2
	s_cmp_lt_i32 s6, 0x10000
	s_cselect_b32 s26, 63, 0xff
	s_cselect_b32 s19, 64, 0x100
	s_and_b32 s18, s6, s26
	s_sub_i32 s27, s6, s18
	s_lshl_b32 s27, s27, 10
	v_add_u32_e32 v172, s18, v170
	v_add_u32_e32 v173, s27, v171
	v_subrev_u32_e32 v176, 1, v172
	v_add_u32_e32 v177, 1, v172
	v_max_i32_e32 v176, 0, v176
	v_min_i32_e32 v177, s19, v177
	v_lshl_add_u32 v187, v172, 10, v173
	v_sub_u32_e32 v178, v177, v176
	global_load_dwordx4 v[0:3], v187, s[22:23]
	v_lshl_add_u32 v188, v176, 10, v173
	v_mov_b32_e32 v136, 1.0
	global_load_dwordx4 v[4:7], v188, s[22:23]
	v_add_u32_e32 v179, 1, v176
	v_cmp_lt_i32_e64 s[30:31], v179, v177
	s_nop 1
	v_cndmask_b32_e64 v183, v172, v179, s[30:31]
	v_cndmask_b32_e64 v137, 0, 1.0, s[30:31]
	v_lshl_add_u32 v187, v183, 10, v173
	global_load_dwordx4 v[8:11], v187, s[22:23]
	v_cvt_f32_i32_e32 v178, v178
	v_div_scale_f32 v212, s[40:41], v178, v178, 1.0
	v_div_scale_f32 v215, vcc, 1.0, v178, 1.0
	v_rcp_f32_e32 v213, v212
	s_nop 0
	v_fma_f32 v214, -v212, v213, 1.0
	v_fmac_f32_e32 v213, v214, v213
	v_mul_f32_e32 v216, v215, v213
	v_fma_f32 v217, -v212, v216, v215
	v_fmac_f32_e32 v216, v217, v213
	v_fma_f32 v218, -v212, v216, v215
	v_div_fmas_f32 v219, v218, v213, v216
	v_div_fixup_f32 v166, v219, v178, 1.0
	v_subrev_u32_e32 v176, 2, v172
	v_add_u32_e32 v177, 2, v172
	v_max_i32_e32 v176, 0, v176
	v_min_i32_e32 v177, s19, v177
	v_lshl_add_u32 v187, v172, 10, v173
	v_sub_u32_e32 v178, v177, v176
	global_load_dwordx4 v[12:15], v187, s[22:23] offset:256
	v_lshl_add_u32 v188, v176, 10, v173
	v_mov_b32_e32 v138, 1.0
	global_load_dwordx4 v[16:19], v188, s[22:23] offset:256
	v_add_u32_e32 v179, 1, v176
	v_add_u32_e32 v180, 2, v176
	v_add_u32_e32 v181, 3, v176
	v_cmp_lt_i32_e64 s[30:31], v179, v177
	v_cmp_lt_i32_e64 s[34:35], v180, v177
	v_cmp_lt_i32_e64 s[36:37], v181, v177
	v_cndmask_b32_e64 v183, v172, v179, s[30:31]
	v_cndmask_b32_e64 v139, 0, 1.0, s[30:31]
	v_lshl_add_u32 v187, v183, 10, v173
	global_load_dwordx4 v[20:23], v187, s[22:23] offset:256
	v_cndmask_b32_e64 v184, v172, v180, s[34:35]
	v_cndmask_b32_e64 v140, 0, 1.0, s[34:35]
	v_lshl_add_u32 v188, v184, 10, v173
	global_load_dwordx4 v[24:27], v188, s[22:23] offset:256
	v_cndmask_b32_e64 v185, v172, v181, s[36:37]
	v_cndmask_b32_e64 v141, 0, 1.0, s[36:37]
	v_lshl_add_u32 v189, v185, 10, v173
	global_load_dwordx4 v[28:31], v189, s[22:23] offset:256
	v_cvt_f32_i32_e32 v178, v178
	v_div_scale_f32 v212, s[40:41], v178, v178, 1.0
	v_div_scale_f32 v215, vcc, 1.0, v178, 1.0
	v_rcp_f32_e32 v213, v212
	s_nop 0
	v_fma_f32 v214, -v212, v213, 1.0
	v_fmac_f32_e32 v213, v214, v213
	v_mul_f32_e32 v216, v215, v213
	v_fma_f32 v217, -v212, v216, v215
	v_fmac_f32_e32 v216, v217, v213
	v_fma_f32 v218, -v212, v216, v215
	v_div_fmas_f32 v219, v218, v213, v216
	v_div_fixup_f32 v167, v219, v178, 1.0
	v_subrev_u32_e32 v176, 4, v172
	v_add_u32_e32 v177, 4, v172
	v_max_i32_e32 v176, 0, v176
	v_min_i32_e32 v177, s19, v177
	v_lshl_add_u32 v187, v172, 10, v173
	v_sub_u32_e32 v178, v177, v176
	global_load_dwordx4 v[32:35], v187, s[22:23] offset:512
	v_lshl_add_u32 v188, v176, 10, v173
	v_mov_b32_e32 v142, 1.0
	global_load_dwordx4 v[36:39], v188, s[22:23] offset:512
	v_add_u32_e32 v179, 1, v176
	v_add_u32_e32 v180, 2, v176
	v_add_u32_e32 v181, 3, v176
	v_add_u32_e32 v182, 4, v176
	v_cmp_lt_i32_e64 s[30:31], v179, v177
	v_cmp_lt_i32_e64 s[34:35], v180, v177
	v_cmp_lt_i32_e64 s[36:37], v181, v177
	v_cmp_lt_i32_e64 s[38:39], v182, v177
	v_cndmask_b32_e64 v183, v172, v179, s[30:31]
	v_cndmask_b32_e64 v143, 0, 1.0, s[30:31]
	v_lshl_add_u32 v187, v183, 10, v173
	global_load_dwordx4 v[40:43], v187, s[22:23] offset:512
	v_cndmask_b32_e64 v184, v172, v180, s[34:35]
	v_cndmask_b32_e64 v144, 0, 1.0, s[34:35]
	v_lshl_add_u32 v188, v184, 10, v173
	global_load_dwordx4 v[44:47], v188, s[22:23] offset:512
	v_cndmask_b32_e64 v185, v172, v181, s[36:37]
	v_cndmask_b32_e64 v145, 0, 1.0, s[36:37]
	v_lshl_add_u32 v189, v185, 10, v173
	global_load_dwordx4 v[48:51], v189, s[22:23] offset:512
	v_cndmask_b32_e64 v186, v172, v182, s[38:39]
	v_cndmask_b32_e64 v146, 0, 1.0, s[38:39]
	v_lshl_add_u32 v190, v186, 10, v173
	global_load_dwordx4 v[52:55], v190, s[22:23] offset:512
	v_add_u32_e32 v179, 5, v176
	v_add_u32_e32 v180, 6, v176
	v_add_u32_e32 v181, 7, v176
	v_cmp_lt_i32_e64 s[30:31], v179, v177
	v_cmp_lt_i32_e64 s[34:35], v180, v177
	v_cmp_lt_i32_e64 s[36:37], v181, v177
	v_cndmask_b32_e64 v183, v172, v179, s[30:31]
	v_cndmask_b32_e64 v147, 0, 1.0, s[30:31]
	v_lshl_add_u32 v187, v183, 10, v173
	global_load_dwordx4 v[56:59], v187, s[22:23] offset:512
	v_cndmask_b32_e64 v184, v172, v180, s[34:35]
	v_cndmask_b32_e64 v148, 0, 1.0, s[34:35]
	v_lshl_add_u32 v188, v184, 10, v173
	global_load_dwordx4 v[60:63], v188, s[22:23] offset:512
	v_cndmask_b32_e64 v185, v172, v181, s[36:37]
	v_cndmask_b32_e64 v149, 0, 1.0, s[36:37]
	v_lshl_add_u32 v189, v185, 10, v173
	global_load_dwordx4 v[64:67], v189, s[22:23] offset:512
	v_cvt_f32_i32_e32 v178, v178
	v_div_scale_f32 v212, s[40:41], v178, v178, 1.0
	v_div_scale_f32 v215, vcc, 1.0, v178, 1.0
	v_rcp_f32_e32 v213, v212
	s_nop 0
	v_fma_f32 v214, -v212, v213, 1.0
; __device__ __forceinline__ float bflo(unsigned u) { return __uint_as_float(u << 16); }
; __device__ __forceinline__ float bfhi(unsigned u) { return __uint_as_float(u & 0xffff0000u); }
; template <int l> __device__ __forceinline__ void layer_body(LAS unsigned char* lds, const int wave_s) {
;     ...
;         for (int row = gw; row < rows_post; row += NGW) {
;             int pos, Ls; if (row < TL) { pos = row & 63; Ls = 64; } else { pos = (row - TL) & 255; Ls = 256; }
;             const int hw = 1 << (lane >> 4);
;             const int lo = max(pos - hw, 0), hi = min(pos + hw, Ls);
;             const bf16* base = POOLb + (size_t)(row - pos) * 512 + 8 * lane;
;             float s[8];
; #pragma unroll
;             for (int e = 0; e < 8; ++e) s[e] = 0.f;
;             v4u av[16];
; #pragma unroll
;             for (int k = 0; k < 16; ++k) { const int p = lo + k; const int pc = p < hi ? p : pos; av[k] = *(const v4u*)(base + (size_t)pc * 512); }
; #pragma unroll
;             for (int k = 0; k < 16; ++k) { const float vm = (lo + k < hi) ? 1.f : 0.f; const v4u a = av[k];
;                 s[0] += vm * bflo(a.x); s[1] += vm * bfhi(a.x); s[2] += vm * bflo(a.y); s[3] += vm * bfhi(a.y); s[4] += vm * bflo(a.z); s[5] += vm * bfhi(a.z); s[6] += vm * bflo(a.w); s[7] += vm * bfhi(a.w); }
;             const v4u me = *(const v4u*)(base + (size_t)pos * 512); const float inv = 1.0f / (float)(hi - lo);
	v_fmac_f32_e32 v213, v214, v213
	v_mul_f32_e32 v216, v215, v213
	v_fma_f32 v217, -v212, v216, v215
	v_fmac_f32_e32 v216, v217, v213
	v_fma_f32 v218, -v212, v216, v215
	v_div_fmas_f32 v219, v218, v213, v216
	v_div_fixup_f32 v168, v219, v178, 1.0
	v_subrev_u32_e32 v176, 8, v172
	v_add_u32_e32 v177, 8, v172
	v_max_i32_e32 v176, 0, v176
	v_min_i32_e32 v177, s19, v177
	v_lshl_add_u32 v187, v172, 10, v173
	v_sub_u32_e32 v178, v177, v176
	global_load_dwordx4 v[68:71], v187, s[22:23] offset:768
	v_lshl_add_u32 v188, v176, 10, v173
	v_mov_b32_e32 v150, 1.0
	global_load_dwordx4 v[72:75], v188, s[22:23] offset:768
	v_add_u32_e32 v179, 1, v176
	v_add_u32_e32 v180, 2, v176
	v_add_u32_e32 v181, 3, v176
	v_add_u32_e32 v182, 4, v176
	v_cmp_lt_i32_e64 s[30:31], v179, v177
	v_cmp_lt_i32_e64 s[34:35], v180, v177
	v_cmp_lt_i32_e64 s[36:37], v181, v177
	v_cmp_lt_i32_e64 s[38:39], v182, v177
	v_cndmask_b32_e64 v183, v172, v179, s[30:31]
	v_cndmask_b32_e64 v151, 0, 1.0, s[30:31]
	v_lshl_add_u32 v187, v183, 10, v173
	global_load_dwordx4 v[76:79], v187, s[22:23] offset:768
	v_cndmask_b32_e64 v184, v172, v180, s[34:35]
	v_cndmask_b32_e64 v152, 0, 1.0, s[34:35]
	v_lshl_add_u32 v188, v184, 10, v173
	global_load_dwordx4 v[80:83], v188, s[22:23] offset:768
	v_cndmask_b32_e64 v185, v172, v181, s[36:37]
	v_cndmask_b32_e64 v153, 0, 1.0, s[36:37]
	v_lshl_add_u32 v189, v185, 10, v173
	global_load_dwordx4 v[84:87], v189, s[22:23] offset:768
	v_cndmask_b32_e64 v186, v172, v182, s[38:39]
	v_cndmask_b32_e64 v154, 0, 1.0, s[38:39]
	v_lshl_add_u32 v190, v186, 10, v173
	global_load_dwordx4 v[88:91], v190, s[22:23] offset:768
	v_add_u32_e32 v179, 5, v176
	v_add_u32_e32 v180, 6, v176
	v_add_u32_e32 v181, 7, v176
	v_add_u32_e32 v182, 8, v176
	v_cmp_lt_i32_e64 s[30:31], v179, v177
	v_cmp_lt_i32_e64 s[34:35], v180, v177
	v_cmp_lt_i32_e64 s[36:37], v181, v177
	v_cmp_lt_i32_e64 s[38:39], v182, v177
	v_cndmask_b32_e64 v183, v172, v179, s[30:31]
	v_cndmask_b32_e64 v155, 0, 1.0, s[30:31]
	v_lshl_add_u32 v187, v183, 10, v173
	global_load_dwordx4 v[92:95], v187, s[22:23] offset:768
	v_cndmask_b32_e64 v184, v172, v180, s[34:35]
	v_cndmask_b32_e64 v156, 0, 1.0, s[34:35]
	v_lshl_add_u32 v188, v184, 10, v173
	global_load_dwordx4 v[96:99], v188, s[22:23] offset:768
	v_cndmask_b32_e64 v185, v172, v181, s[36:37]
	v_cndmask_b32_e64 v157, 0, 1.0, s[36:37]
	v_lshl_add_u32 v189, v185, 10, v173
	global_load_dwordx4 v[100:103], v189, s[22:23] offset:768
	v_cndmask_b32_e64 v186, v172, v182, s[38:39]
	v_cndmask_b32_e64 v158, 0, 1.0, s[38:39]
	v_lshl_add_u32 v190, v186, 10, v173
	global_load_dwordx4 v[104:107], v190, s[22:23] offset:768
	v_add_u32_e32 v179, 9, v176
	v_add_u32_e32 v180, 10, v176
	v_add_u32_e32 v181, 11, v176
	v_add_u32_e32 v182, 12, v176
	v_cmp_lt_i32_e64 s[30:31], v179, v177
	v_cmp_lt_i32_e64 s[34:35], v180, v177
	v_cmp_lt_i32_e64 s[36:37], v181, v177
	v_cmp_lt_i32_e64 s[38:39], v182, v177
	v_cndmask_b32_e64 v183, v172, v179, s[30:31]
	v_cndmask_b32_e64 v159, 0, 1.0, s[30:31]
	v_lshl_add_u32 v187, v183, 10, v173
	global_load_dwordx4 v[108:111], v187, s[22:23] offset:768
	v_cndmask_b32_e64 v184, v172, v180, s[34:35]
	v_cndmask_b32_e64 v160, 0, 1.0, s[34:35]
	v_lshl_add_u32 v188, v184, 10, v173
	global_load_dwordx4 v[112:115], v188, s[22:23] offset:768
	v_cndmask_b32_e64 v185, v172, v181, s[36:37]
	v_cndmask_b32_e64 v161, 0, 1.0, s[36:37]
	v_lshl_add_u32 v189, v185, 10, v173
	global_load_dwordx4 v[116:119], v189, s[22:23] offset:768
	v_cndmask_b32_e64 v186, v172, v182, s[38:39]
	v_cndmask_b32_e64 v162, 0, 1.0, s[38:39]
	v_lshl_add_u32 v190, v186, 10, v173
	global_load_dwordx4 v[120:123], v190, s[22:23] offset:768
	v_add_u32_e32 v179, 13, v176
	v_add_u32_e32 v180, 14, v176
	v_add_u32_e32 v181, 15, v176
	v_cmp_lt_i32_e64 s[30:31], v179, v177
	v_cmp_lt_i32_e64 s[34:35], v180, v177
	v_cmp_lt_i32_e64 s[36:37], v181, v177
	v_cndmask_b32_e64 v183, v172, v179, s[30:31]
	v_cndmask_b32_e64 v163, 0, 1.0, s[30:31]
	v_lshl_add_u32 v187, v183, 10, v173
	global_load_dwordx4 v[124:127], v187, s[22:23] offset:768
	v_cndmask_b32_e64 v184, v172, v180, s[34:35]
	v_cndmask_b32_e64 v164, 0, 1.0, s[34:35]
	v_lshl_add_u32 v188, v184, 10, v173
	global_load_dwordx4 v[128:131], v188, s[22:23] offset:768
	v_cndmask_b32_e64 v185, v172, v181, s[36:37]
	v_cndmask_b32_e64 v165, 0, 1.0, s[36:37]
	v_lshl_add_u32 v189, v185, 10, v173
	global_load_dwordx4 v[132:135], v189, s[22:23] offset:768
	v_cvt_f32_i32_e32 v178, v178
	v_div_scale_f32 v212, s[40:41], v178, v178, 1.0
	v_div_scale_f32 v215, vcc, 1.0, v178, 1.0
	v_rcp_f32_e32 v213, v212
	s_nop 0
	v_fma_f32 v214, -v212, v213, 1.0
	v_fmac_f32_e32 v213, v214, v213
	v_mul_f32_e32 v216, v215, v213
	v_fma_f32 v217, -v212, v216, v215
	v_fmac_f32_e32 v216, v217, v213
	v_fma_f32 v218, -v212, v216, v215
	v_div_fmas_f32 v219, v218, v213, v216
	v_div_fixup_f32 v169, v219, v178, 1.0
; __device__ __forceinline__ unsigned cvtpk(float lo, float hi) { f32x2 v = {lo, hi}; bf16x2_t b = __builtin_convertvector(v, bf16x2_t); return __builtin_bit_cast(unsigned, b); }
; __device__ __forceinline__ float bflo(unsigned u) { return __uint_as_float(u << 16); }
; __device__ __forceinline__ float bfhi(unsigned u) { return __uint_as_float(u & 0xffff0000u); }
; template <int l> __device__ __forceinline__ void layer_body(LAS unsigned char* lds, const int wave_s) {
;     ...
;         for (int row = gw; row < rows_post; row += NGW) {
;             int pos, Ls; if (row < TL) { pos = row & 63; Ls = 64; } else { pos = (row - TL) & 255; Ls = 256; }
;             const int hw = 1 << (lane >> 4);
;             const int lo = max(pos - hw, 0), hi = min(pos + hw, Ls);
;             const bf16* base = POOLb + (size_t)(row - pos) * 512 + 8 * lane;
;             float s[8];
; #pragma unroll
;             for (int e = 0; e < 8; ++e) s[e] = 0.f;
;             v4u av[16];
; #pragma unroll
;             for (int k = 0; k < 16; ++k) { const int p = lo + k; const int pc = p < hi ? p : pos; av[k] = *(const v4u*)(base + (size_t)pc * 512); }
; #pragma unroll
;             for (int k = 0; k < 16; ++k) { const float vm = (lo + k < hi) ? 1.f : 0.f; const v4u a = av[k];
;                 s[0] += vm * bflo(a.x); s[1] += vm * bfhi(a.x); s[2] += vm * bflo(a.y); s[3] += vm * bfhi(a.y); s[4] += vm * bflo(a.z); s[5] += vm * bfhi(a.z); s[6] += vm * bflo(a.w); s[7] += vm * bfhi(a.w); }
;             const v4u me = *(const v4u*)(base + (size_t)pos * 512); const float inv = 1.0f / (float)(hi - lo);
;             v4u w; w.x = cvtpk(s[0] * inv - bflo(me.x), s[1] * inv - bfhi(me.x)); w.y = cvtpk(s[2] * inv - bflo(me.y), s[3] * inv - bfhi(me.y));
;             w.z = cvtpk(s[4] * inv - bflo(me.z), s[5] * inv - bfhi(me.z)); w.w = cvtpk(s[6] * inv - bflo(me.w), s[7] * inv - bfhi(me.w));
;             *(v4u*)(POOLEDb + (size_t)row * 512 + 8 * lane) = w;
.Lc1_loop_L3:
	s_lshl_b32 s28, s4, 12
	v_add_u32_e32 v175, s28, v174
	s_add_i32 s5, s4, s96
	s_cmp_lt_i32 s5, 0x4000
	s_cselect_b32 s5, s5, s4
	s_cselect_b32 s29, 1, 0
	s_waitcnt vmcnt(31)
	v_lshlrev_b32_e32 v199, 16, v4
	v_and_b32_e32 v200, 0xffff0000, v4
	v_lshlrev_b32_e32 v201, 16, v5
	v_and_b32_e32 v202, 0xffff0000, v5
	v_lshlrev_b32_e32 v203, 16, v6
	v_and_b32_e32 v204, 0xffff0000, v6
	v_lshlrev_b32_e32 v205, 16, v7
	v_and_b32_e32 v206, 0xffff0000, v7
	v_fma_f32 v191, v136, v199, 0
	v_fma_f32 v192, v136, v200, 0
	v_fma_f32 v193, v136, v201, 0
	v_fma_f32 v194, v136, v202, 0
	v_fma_f32 v195, v136, v203, 0
	v_fma_f32 v196, v136, v204, 0
	v_fma_f32 v197, v136, v205, 0
	v_fma_f32 v198, v136, v206, 0
	v_lshlrev_b32_e32 v199, 16, v8
	v_and_b32_e32 v200, 0xffff0000, v8
	v_lshlrev_b32_e32 v201, 16, v9
	v_and_b32_e32 v202, 0xffff0000, v9
	v_lshlrev_b32_e32 v203, 16, v10
	v_and_b32_e32 v204, 0xffff0000, v10
	v_lshlrev_b32_e32 v205, 16, v11
	v_and_b32_e32 v206, 0xffff0000, v11
	v_fma_f32 v191, v137, v199, v191
	v_fma_f32 v192, v137, v200, v192
	v_fma_f32 v193, v137, v201, v193
	v_fma_f32 v194, v137, v202, v194
	v_fma_f32 v195, v137, v203, v195
	v_fma_f32 v196, v137, v204, v196
	v_fma_f32 v197, v137, v205, v197
	v_fma_f32 v198, v137, v206, v198
	v_lshlrev_b32_e32 v199, 16, v0
	v_and_b32_e32 v200, 0xffff0000, v0
	v_lshlrev_b32_e32 v201, 16, v1
	v_and_b32_e32 v202, 0xffff0000, v1
	v_lshlrev_b32_e32 v203, 16, v2
	v_and_b32_e32 v204, 0xffff0000, v2
	v_lshlrev_b32_e32 v205, 16, v3
	v_and_b32_e32 v206, 0xffff0000, v3
	v_fma_f32 v191, v166, v191, -v199
	v_fma_f32 v192, v166, v192, -v200
	v_fma_f32 v193, v166, v193, -v201
	v_fma_f32 v194, v166, v194, -v202
	v_fma_f32 v195, v166, v195, -v203
	v_fma_f32 v196, v166, v196, -v204
	v_fma_f32 v197, v166, v197, -v205
	v_fma_f32 v198, v166, v198, -v206
	v_cvt_pk_bf16_f32 v208, v191, v192
	v_cvt_pk_bf16_f32 v209, v193, v194
	v_cvt_pk_bf16_f32 v210, v195, v196
	v_cvt_pk_bf16_f32 v211, v197, v198
	global_store_dwordx4 v175, v[208:211], s[24:25]
	s_mov_b32 s4, s5
	s_lshl_b32 s6, s4, 2
	s_cmp_lt_i32 s6, 0x10000
	s_cselect_b32 s26, 63, 0xff
	s_cselect_b32 s19, 64, 0x100
	s_and_b32 s18, s6, s26
	s_sub_i32 s27, s6, s18
	s_lshl_b32 s27, s27, 10
	v_add_u32_e32 v172, s18, v170
	v_add_u32_e32 v173, s27, v171
	v_subrev_u32_e32 v176, 1, v172
	v_add_u32_e32 v177, 1, v172
	v_max_i32_e32 v176, 0, v176
	v_min_i32_e32 v177, s19, v177
	v_lshl_add_u32 v187, v172, 10, v173
	v_sub_u32_e32 v178, v177, v176
	global_load_dwordx4 v[0:3], v187, s[22:23]
	v_lshl_add_u32 v188, v176, 10, v173
	v_mov_b32_e32 v136, 1.0
	global_load_dwordx4 v[4:7], v188, s[22:23]
	v_add_u32_e32 v179, 1, v176
	v_cmp_lt_i32_e64 s[30:31], v179, v177
	s_nop 1
	v_cndmask_b32_e64 v183, v172, v179, s[30:31]
	v_cndmask_b32_e64 v137, 0, 1.0, s[30:31]
	v_lshl_add_u32 v187, v183, 10, v173
	global_load_dwordx4 v[8:11], v187, s[22:23]
	v_cvt_f32_i32_e32 v178, v178
	v_div_scale_f32 v212, s[40:41], v178, v178, 1.0
	v_div_scale_f32 v215, vcc, 1.0, v178, 1.0
	v_rcp_f32_e32 v213, v212
	s_nop 0
	v_fma_f32 v214, -v212, v213, 1.0
	v_fmac_f32_e32 v213, v214, v213
	v_mul_f32_e32 v216, v215, v213
	v_fma_f32 v217, -v212, v216, v215
	v_fmac_f32_e32 v216, v217, v213
	v_fma_f32 v218, -v212, v216, v215
	v_div_fmas_f32 v219, v218, v213, v216
	v_div_fixup_f32 v166, v219, v178, 1.0
	s_waitcnt vmcnt(30)
	v_lshlrev_b32_e32 v199, 16, v16
	v_and_b32_e32 v200, 0xffff0000, v16
	v_lshlrev_b32_e32 v201, 16, v17
	v_and_b32_e32 v202, 0xffff0000, v17
	v_lshlrev_b32_e32 v203, 16, v18
	v_and_b32_e32 v204, 0xffff0000, v18
	v_lshlrev_b32_e32 v205, 16, v19
	v_and_b32_e32 v206, 0xffff0000, v19
	v_fma_f32 v191, v138, v199, 0
	v_fma_f32 v192, v138, v200, 0
	v_fma_f32 v193, v138, v201, 0
	v_fma_f32 v194, v138, v202, 0
	v_fma_f32 v195, v138, v203, 0
	v_fma_f32 v196, v138, v204, 0
	v_fma_f32 v197, v138, v205, 0
	v_fma_f32 v198, v138, v206, 0
	v_lshlrev_b32_e32 v199, 16, v20
	v_and_b32_e32 v200, 0xffff0000, v20
	v_lshlrev_b32_e32 v201, 16, v21
	v_and_b32_e32 v202, 0xffff0000, v21
	v_lshlrev_b32_e32 v203, 16, v22
	v_and_b32_e32 v204, 0xffff0000, v22
	v_lshlrev_b32_e32 v205, 16, v23
	v_and_b32_e32 v206, 0xffff0000, v23
	v_fma_f32 v191, v139, v199, v191
	v_fma_f32 v192, v139, v200, v192
	v_fma_f32 v193, v139, v201, v193
	v_fma_f32 v194, v139, v202, v194
	v_fma_f32 v195, v139, v203, v195
	v_fma_f32 v196, v139, v204, v196
	v_fma_f32 v197, v139, v205, v197
	v_fma_f32 v198, v139, v206, v198
	v_lshlrev_b32_e32 v199, 16, v24
	v_and_b32_e32 v200, 0xffff0000, v24
	v_lshlrev_b32_e32 v201, 16, v25
	v_and_b32_e32 v202, 0xffff0000, v25
	v_lshlrev_b32_e32 v203, 16, v26
	v_and_b32_e32 v204, 0xffff0000, v26
	v_lshlrev_b32_e32 v205, 16, v27
	v_and_b32_e32 v206, 0xffff0000, v27
	v_fma_f32 v191, v140, v199, v191
	v_fma_f32 v192, v140, v200, v192
	v_fma_f32 v193, v140, v201, v193
	v_fma_f32 v194, v140, v202, v194
	v_fma_f32 v195, v140, v203, v195
	v_fma_f32 v196, v140, v204, v196
	v_fma_f32 v197, v140, v205, v197
	v_fma_f32 v198, v140, v206, v198
	v_lshlrev_b32_e32 v199, 16, v28
	v_and_b32_e32 v200, 0xffff0000, v28
	v_lshlrev_b32_e32 v201, 16, v29
	v_and_b32_e32 v202, 0xffff0000, v29
	v_lshlrev_b32_e32 v203, 16, v30
	v_and_b32_e32 v204, 0xffff0000, v30
	v_lshlrev_b32_e32 v205, 16, v31
	v_and_b32_e32 v206, 0xffff0000, v31
	v_fma_f32 v191, v141, v199, v191
	v_fma_f32 v192, v141, v200, v192
	v_fma_f32 v193, v141, v201, v193
	v_fma_f32 v194, v141, v202, v194
	v_fma_f32 v195, v141, v203, v195
	v_fma_f32 v196, v141, v204, v196
	v_fma_f32 v197, v141, v205, v197
	v_fma_f32 v198, v141, v206, v198
	v_lshlrev_b32_e32 v199, 16, v12
	v_and_b32_e32 v200, 0xffff0000, v12
	v_lshlrev_b32_e32 v201, 16, v13
	v_and_b32_e32 v202, 0xffff0000, v13
; __device__ __forceinline__ unsigned cvtpk(float lo, float hi) { f32x2 v = {lo, hi}; bf16x2_t b = __builtin_convertvector(v, bf16x2_t); return __builtin_bit_cast(unsigned, b); }
; __device__ __forceinline__ float bflo(unsigned u) { return __uint_as_float(u << 16); }
; __device__ __forceinline__ float bfhi(unsigned u) { return __uint_as_float(u & 0xffff0000u); }
; template <int l> __device__ __forceinline__ void layer_body(LAS unsigned char* lds, const int wave_s) {
;     ...
;         for (int row = gw; row < rows_post; row += NGW) {
;             int pos, Ls; if (row < TL) { pos = row & 63; Ls = 64; } else { pos = (row - TL) & 255; Ls = 256; }
;             const int hw = 1 << (lane >> 4);
;             const int lo = max(pos - hw, 0), hi = min(pos + hw, Ls);
;             const bf16* base = POOLb + (size_t)(row - pos) * 512 + 8 * lane;
;             float s[8];
; #pragma unroll
;             for (int e = 0; e < 8; ++e) s[e] = 0.f;
;             v4u av[16];
; #pragma unroll
;             for (int k = 0; k < 16; ++k) { const int p = lo + k; const int pc = p < hi ? p : pos; av[k] = *(const v4u*)(base + (size_t)pc * 512); }
; #pragma unroll
;             for (int k = 0; k < 16; ++k) { const float vm = (lo + k < hi) ? 1.f : 0.f; const v4u a = av[k];
;                 s[0] += vm * bflo(a.x); s[1] += vm * bfhi(a.x); s[2] += vm * bflo(a.y); s[3] += vm * bfhi(a.y); s[4] += vm * bflo(a.z); s[5] += vm * bfhi(a.z); s[6] += vm * bflo(a.w); s[7] += vm * bfhi(a.w); }
;             const v4u me = *(const v4u*)(base + (size_t)pos * 512); const float inv = 1.0f / (float)(hi - lo);
;             v4u w; w.x = cvtpk(s[0] * inv - bflo(me.x), s[1] * inv - bfhi(me.x)); w.y = cvtpk(s[2] * inv - bflo(me.y), s[3] * inv - bfhi(me.y));
;             w.z = cvtpk(s[4] * inv - bflo(me.z), s[5] * inv - bfhi(me.z)); w.w = cvtpk(s[6] * inv - bflo(me.w), s[7] * inv - bfhi(me.w));
;             *(v4u*)(POOLEDb + (size_t)row * 512 + 8 * lane) = w;
	v_lshlrev_b32_e32 v203, 16, v14
	v_and_b32_e32 v204, 0xffff0000, v14
	v_lshlrev_b32_e32 v205, 16, v15
	v_and_b32_e32 v206, 0xffff0000, v15
	v_fma_f32 v191, v167, v191, -v199
	v_fma_f32 v192, v167, v192, -v200
	v_fma_f32 v193, v167, v193, -v201
	v_fma_f32 v194, v167, v194, -v202
	v_fma_f32 v195, v167, v195, -v203
	v_fma_f32 v196, v167, v196, -v204
	v_fma_f32 v197, v167, v197, -v205
	v_fma_f32 v198, v167, v198, -v206
	v_cvt_pk_bf16_f32 v208, v191, v192
	v_cvt_pk_bf16_f32 v209, v193, v194
	v_cvt_pk_bf16_f32 v210, v195, v196
	v_cvt_pk_bf16_f32 v211, v197, v198
	global_store_dwordx4 v175, v[208:211], s[24:25] offset:256
	v_subrev_u32_e32 v176, 2, v172
	v_add_u32_e32 v177, 2, v172
	v_max_i32_e32 v176, 0, v176
	v_min_i32_e32 v177, s19, v177
	v_lshl_add_u32 v187, v172, 10, v173
	v_sub_u32_e32 v178, v177, v176
	global_load_dwordx4 v[12:15], v187, s[22:23] offset:256
	v_lshl_add_u32 v188, v176, 10, v173
	v_mov_b32_e32 v138, 1.0
	global_load_dwordx4 v[16:19], v188, s[22:23] offset:256
	v_add_u32_e32 v179, 1, v176
	v_add_u32_e32 v180, 2, v176
	v_add_u32_e32 v181, 3, v176
	v_cmp_lt_i32_e64 s[30:31], v179, v177
	v_cmp_lt_i32_e64 s[34:35], v180, v177
	v_cmp_lt_i32_e64 s[36:37], v181, v177
	v_cndmask_b32_e64 v183, v172, v179, s[30:31]
	v_cndmask_b32_e64 v139, 0, 1.0, s[30:31]
	v_lshl_add_u32 v187, v183, 10, v173
	global_load_dwordx4 v[20:23], v187, s[22:23] offset:256
	v_cndmask_b32_e64 v184, v172, v180, s[34:35]
	v_cndmask_b32_e64 v140, 0, 1.0, s[34:35]
	v_lshl_add_u32 v188, v184, 10, v173
	global_load_dwordx4 v[24:27], v188, s[22:23] offset:256
	v_cndmask_b32_e64 v185, v172, v181, s[36:37]
	v_cndmask_b32_e64 v141, 0, 1.0, s[36:37]
	v_lshl_add_u32 v189, v185, 10, v173
	global_load_dwordx4 v[28:31], v189, s[22:23] offset:256
	v_cvt_f32_i32_e32 v178, v178
	v_div_scale_f32 v212, s[40:41], v178, v178, 1.0
	v_div_scale_f32 v215, vcc, 1.0, v178, 1.0
	v_rcp_f32_e32 v213, v212
	s_nop 0
	v_fma_f32 v214, -v212, v213, 1.0
	v_fmac_f32_e32 v213, v214, v213
	v_mul_f32_e32 v216, v215, v213
	v_fma_f32 v217, -v212, v216, v215
	v_fmac_f32_e32 v216, v217, v213
	v_fma_f32 v218, -v212, v216, v215
	v_div_fmas_f32 v219, v218, v213, v216
	v_div_fixup_f32 v167, v219, v178, 1.0
	s_waitcnt vmcnt(27)
	v_lshlrev_b32_e32 v199, 16, v36
	v_and_b32_e32 v200, 0xffff0000, v36
	v_lshlrev_b32_e32 v201, 16, v37
	v_and_b32_e32 v202, 0xffff0000, v37
	v_lshlrev_b32_e32 v203, 16, v38
	v_and_b32_e32 v204, 0xffff0000, v38
	v_lshlrev_b32_e32 v205, 16, v39
	v_and_b32_e32 v206, 0xffff0000, v39
	v_fma_f32 v191, v142, v199, 0
	v_fma_f32 v192, v142, v200, 0
	v_fma_f32 v193, v142, v201, 0
	v_fma_f32 v194, v142, v202, 0
	v_fma_f32 v195, v142, v203, 0
	v_fma_f32 v196, v142, v204, 0
	v_fma_f32 v197, v142, v205, 0
	v_fma_f32 v198, v142, v206, 0
	v_lshlrev_b32_e32 v199, 16, v40
	v_and_b32_e32 v200, 0xffff0000, v40
	v_lshlrev_b32_e32 v201, 16, v41
	v_and_b32_e32 v202, 0xffff0000, v41
	v_lshlrev_b32_e32 v203, 16, v42
	v_and_b32_e32 v204, 0xffff0000, v42
	v_lshlrev_b32_e32 v205, 16, v43
	v_and_b32_e32 v206, 0xffff0000, v43
	v_fma_f32 v191, v143, v199, v191
	v_fma_f32 v192, v143, v200, v192
	v_fma_f32 v193, v143, v201, v193
	v_fma_f32 v194, v143, v202, v194
	v_fma_f32 v195, v143, v203, v195
	v_fma_f32 v196, v143, v204, v196
	v_fma_f32 v197, v143, v205, v197
	v_fma_f32 v198, v143, v206, v198
	v_lshlrev_b32_e32 v199, 16, v44
	v_and_b32_e32 v200, 0xffff0000, v44
	v_lshlrev_b32_e32 v201, 16, v45
	v_and_b32_e32 v202, 0xffff0000, v45
	v_lshlrev_b32_e32 v203, 16, v46
	v_and_b32_e32 v204, 0xffff0000, v46
	v_lshlrev_b32_e32 v205, 16, v47
	v_and_b32_e32 v206, 0xffff0000, v47
	v_fma_f32 v191, v144, v199, v191
	v_fma_f32 v192, v144, v200, v192
	v_fma_f32 v193, v144, v201, v193
	v_fma_f32 v194, v144, v202, v194
	v_fma_f32 v195, v144, v203, v195
	v_fma_f32 v196, v144, v204, v196
	v_fma_f32 v197, v144, v205, v197
	v_fma_f32 v198, v144, v206, v198
	v_lshlrev_b32_e32 v199, 16, v48
	v_and_b32_e32 v200, 0xffff0000, v48
	v_lshlrev_b32_e32 v201, 16, v49
	v_and_b32_e32 v202, 0xffff0000, v49
	v_lshlrev_b32_e32 v203, 16, v50
	v_and_b32_e32 v204, 0xffff0000, v50
	v_lshlrev_b32_e32 v205, 16, v51
	v_and_b32_e32 v206, 0xffff0000, v51
	v_fma_f32 v191, v145, v199, v191
	v_fma_f32 v192, v145, v200, v192
	v_fma_f32 v193, v145, v201, v193
	v_fma_f32 v194, v145, v202, v194
	v_fma_f32 v195, v145, v203, v195
	v_fma_f32 v196, v145, v204, v196
	v_fma_f32 v197, v145, v205, v197
	v_fma_f32 v198, v145, v206, v198
	v_lshlrev_b32_e32 v199, 16, v52
	v_and_b32_e32 v200, 0xffff0000, v52
	v_lshlrev_b32_e32 v201, 16, v53
	v_and_b32_e32 v202, 0xffff0000, v53
	v_lshlrev_b32_e32 v203, 16, v54
	v_and_b32_e32 v204, 0xffff0000, v54
	v_lshlrev_b32_e32 v205, 16, v55
	v_and_b32_e32 v206, 0xffff0000, v55
	v_fma_f32 v191, v146, v199, v191
	v_fma_f32 v192, v146, v200, v192
	v_fma_f32 v193, v146, v201, v193
	v_fma_f32 v194, v146, v202, v194
	v_fma_f32 v195, v146, v203, v195
	v_fma_f32 v196, v146, v204, v196
	v_fma_f32 v197, v146, v205, v197
	v_fma_f32 v198, v146, v206, v198
	v_lshlrev_b32_e32 v199, 16, v56
	v_and_b32_e32 v200, 0xffff0000, v56
	v_lshlrev_b32_e32 v201, 16, v57
	v_and_b32_e32 v202, 0xffff0000, v57
	v_lshlrev_b32_e32 v203, 16, v58
	v_and_b32_e32 v204, 0xffff0000, v58
	v_lshlrev_b32_e32 v205, 16, v59
	v_and_b32_e32 v206, 0xffff0000, v59
	v_fma_f32 v191, v147, v199, v191
	v_fma_f32 v192, v147, v200, v192
	v_fma_f32 v193, v147, v201, v193
	v_fma_f32 v194, v147, v202, v194
	v_fma_f32 v195, v147, v203, v195
	v_fma_f32 v196, v147, v204, v196
	v_fma_f32 v197, v147, v205, v197
	v_fma_f32 v198, v147, v206, v198
	v_lshlrev_b32_e32 v199, 16, v60
	v_and_b32_e32 v200, 0xffff0000, v60
	v_lshlrev_b32_e32 v201, 16, v61
	v_and_b32_e32 v202, 0xffff0000, v61
; __device__ __forceinline__ unsigned cvtpk(float lo, float hi) { f32x2 v = {lo, hi}; bf16x2_t b = __builtin_convertvector(v, bf16x2_t); return __builtin_bit_cast(unsigned, b); }
; __device__ __forceinline__ float bflo(unsigned u) { return __uint_as_float(u << 16); }
; __device__ __forceinline__ float bfhi(unsigned u) { return __uint_as_float(u & 0xffff0000u); }
; template <int l> __device__ __forceinline__ void layer_body(LAS unsigned char* lds, const int wave_s) {
;     ...
;         for (int row = gw; row < rows_post; row += NGW) {
;             int pos, Ls; if (row < TL) { pos = row & 63; Ls = 64; } else { pos = (row - TL) & 255; Ls = 256; }
;             const int hw = 1 << (lane >> 4);
;             const int lo = max(pos - hw, 0), hi = min(pos + hw, Ls);
;             const bf16* base = POOLb + (size_t)(row - pos) * 512 + 8 * lane;
;             float s[8];
; #pragma unroll
;             for (int e = 0; e < 8; ++e) s[e] = 0.f;
;             v4u av[16];
; #pragma unroll
;             for (int k = 0; k < 16; ++k) { const int p = lo + k; const int pc = p < hi ? p : pos; av[k] = *(const v4u*)(base + (size_t)pc * 512); }
; #pragma unroll
;             for (int k = 0; k < 16; ++k) { const float vm = (lo + k < hi) ? 1.f : 0.f; const v4u a = av[k];
;                 s[0] += vm * bflo(a.x); s[1] += vm * bfhi(a.x); s[2] += vm * bflo(a.y); s[3] += vm * bfhi(a.y); s[4] += vm * bflo(a.z); s[5] += vm * bfhi(a.z); s[6] += vm * bflo(a.w); s[7] += vm * bfhi(a.w); }
;             const v4u me = *(const v4u*)(base + (size_t)pos * 512); const float inv = 1.0f / (float)(hi - lo);
;             v4u w; w.x = cvtpk(s[0] * inv - bflo(me.x), s[1] * inv - bfhi(me.x)); w.y = cvtpk(s[2] * inv - bflo(me.y), s[3] * inv - bfhi(me.y));
;             w.z = cvtpk(s[4] * inv - bflo(me.z), s[5] * inv - bfhi(me.z)); w.w = cvtpk(s[6] * inv - bflo(me.w), s[7] * inv - bfhi(me.w));
;             *(v4u*)(POOLEDb + (size_t)row * 512 + 8 * lane) = w;
	v_lshlrev_b32_e32 v203, 16, v62
	v_and_b32_e32 v204, 0xffff0000, v62
	v_lshlrev_b32_e32 v205, 16, v63
	v_and_b32_e32 v206, 0xffff0000, v63
	v_fma_f32 v191, v148, v199, v191
	v_fma_f32 v192, v148, v200, v192
	v_fma_f32 v193, v148, v201, v193
	v_fma_f32 v194, v148, v202, v194
	v_fma_f32 v195, v148, v203, v195
	v_fma_f32 v196, v148, v204, v196
	v_fma_f32 v197, v148, v205, v197
	v_fma_f32 v198, v148, v206, v198
	v_lshlrev_b32_e32 v199, 16, v64
	v_and_b32_e32 v200, 0xffff0000, v64
	v_lshlrev_b32_e32 v201, 16, v65
	v_and_b32_e32 v202, 0xffff0000, v65
	v_lshlrev_b32_e32 v203, 16, v66
	v_and_b32_e32 v204, 0xffff0000, v66
	v_lshlrev_b32_e32 v205, 16, v67
	v_and_b32_e32 v206, 0xffff0000, v67
	v_fma_f32 v191, v149, v199, v191
	v_fma_f32 v192, v149, v200, v192
	v_fma_f32 v193, v149, v201, v193
	v_fma_f32 v194, v149, v202, v194
	v_fma_f32 v195, v149, v203, v195
	v_fma_f32 v196, v149, v204, v196
	v_fma_f32 v197, v149, v205, v197
	v_fma_f32 v198, v149, v206, v198
	v_lshlrev_b32_e32 v199, 16, v32
	v_and_b32_e32 v200, 0xffff0000, v32
	v_lshlrev_b32_e32 v201, 16, v33
	v_and_b32_e32 v202, 0xffff0000, v33
	v_lshlrev_b32_e32 v203, 16, v34
	v_and_b32_e32 v204, 0xffff0000, v34
	v_lshlrev_b32_e32 v205, 16, v35
	v_and_b32_e32 v206, 0xffff0000, v35
	v_fma_f32 v191, v168, v191, -v199
	v_fma_f32 v192, v168, v192, -v200
	v_fma_f32 v193, v168, v193, -v201
	v_fma_f32 v194, v168, v194, -v202
	v_fma_f32 v195, v168, v195, -v203
	v_fma_f32 v196, v168, v196, -v204
	v_fma_f32 v197, v168, v197, -v205
	v_fma_f32 v198, v168, v198, -v206
	v_cvt_pk_bf16_f32 v208, v191, v192
	v_cvt_pk_bf16_f32 v209, v193, v194
	v_cvt_pk_bf16_f32 v210, v195, v196
	v_cvt_pk_bf16_f32 v211, v197, v198
	global_store_dwordx4 v175, v[208:211], s[24:25] offset:512
	v_subrev_u32_e32 v176, 4, v172
	v_add_u32_e32 v177, 4, v172
	v_max_i32_e32 v176, 0, v176
	v_min_i32_e32 v177, s19, v177
	v_lshl_add_u32 v187, v172, 10, v173
	v_sub_u32_e32 v178, v177, v176
	global_load_dwordx4 v[32:35], v187, s[22:23] offset:512
	v_lshl_add_u32 v188, v176, 10, v173
	v_mov_b32_e32 v142, 1.0
	global_load_dwordx4 v[36:39], v188, s[22:23] offset:512
	v_add_u32_e32 v179, 1, v176
	v_add_u32_e32 v180, 2, v176
	v_add_u32_e32 v181, 3, v176
	v_add_u32_e32 v182, 4, v176
	v_cmp_lt_i32_e64 s[30:31], v179, v177
	v_cmp_lt_i32_e64 s[34:35], v180, v177
	v_cmp_lt_i32_e64 s[36:37], v181, v177
	v_cmp_lt_i32_e64 s[38:39], v182, v177
	v_cndmask_b32_e64 v183, v172, v179, s[30:31]
	v_cndmask_b32_e64 v143, 0, 1.0, s[30:31]
	v_lshl_add_u32 v187, v183, 10, v173
	global_load_dwordx4 v[40:43], v187, s[22:23] offset:512
	v_cndmask_b32_e64 v184, v172, v180, s[34:35]
	v_cndmask_b32_e64 v144, 0, 1.0, s[34:35]
	v_lshl_add_u32 v188, v184, 10, v173
	global_load_dwordx4 v[44:47], v188, s[22:23] offset:512
	v_cndmask_b32_e64 v185, v172, v181, s[36:37]
	v_cndmask_b32_e64 v145, 0, 1.0, s[36:37]
	v_lshl_add_u32 v189, v185, 10, v173
	global_load_dwordx4 v[48:51], v189, s[22:23] offset:512
	v_cndmask_b32_e64 v186, v172, v182, s[38:39]
	v_cndmask_b32_e64 v146, 0, 1.0, s[38:39]
	v_lshl_add_u32 v190, v186, 10, v173
	global_load_dwordx4 v[52:55], v190, s[22:23] offset:512
	v_add_u32_e32 v179, 5, v176
	v_add_u32_e32 v180, 6, v176
	v_add_u32_e32 v181, 7, v176
	v_cmp_lt_i32_e64 s[30:31], v179, v177
	v_cmp_lt_i32_e64 s[34:35], v180, v177
	v_cmp_lt_i32_e64 s[36:37], v181, v177
	v_cndmask_b32_e64 v183, v172, v179, s[30:31]
	v_cndmask_b32_e64 v147, 0, 1.0, s[30:31]
	v_lshl_add_u32 v187, v183, 10, v173
	global_load_dwordx4 v[56:59], v187, s[22:23] offset:512
	v_cndmask_b32_e64 v184, v172, v180, s[34:35]
	v_cndmask_b32_e64 v148, 0, 1.0, s[34:35]
	v_lshl_add_u32 v188, v184, 10, v173
	global_load_dwordx4 v[60:63], v188, s[22:23] offset:512
	v_cndmask_b32_e64 v185, v172, v181, s[36:37]
	v_cndmask_b32_e64 v149, 0, 1.0, s[36:37]
	v_lshl_add_u32 v189, v185, 10, v173
	global_load_dwordx4 v[64:67], v189, s[22:23] offset:512
	v_cvt_f32_i32_e32 v178, v178
	v_div_scale_f32 v212, s[40:41], v178, v178, 1.0
	v_div_scale_f32 v215, vcc, 1.0, v178, 1.0
	v_rcp_f32_e32 v213, v212
	s_nop 0
	v_fma_f32 v214, -v212, v213, 1.0
	v_fmac_f32_e32 v213, v214, v213
	v_mul_f32_e32 v216, v215, v213
	v_fma_f32 v217, -v212, v216, v215
	v_fmac_f32_e32 v216, v217, v213
	v_fma_f32 v218, -v212, v216, v215
	v_div_fmas_f32 v219, v218, v213, v216
	v_div_fixup_f32 v168, v219, v178, 1.0
	s_waitcnt vmcnt(20)
; __device__ __forceinline__ float bflo(unsigned u) { return __uint_as_float(u << 16); }
; __device__ __forceinline__ float bfhi(unsigned u) { return __uint_as_float(u & 0xffff0000u); }
; template <int l> __device__ __forceinline__ void layer_body(LAS unsigned char* lds, const int wave_s) {
;     ...
;             for (int k = 0; k < 16; ++k) { const float vm = (lo + k < hi) ? 1.f : 0.f; const v4u a = av[k];
;                 s[0] += vm * bflo(a.x); s[1] += vm * bfhi(a.x); s[2] += vm * bflo(a.y); s[3] += vm * bfhi(a.y); s[4] += vm * bflo(a.z); s[5] += vm * bfhi(a.z); s[6] += vm * bflo(a.w); s[7] += vm * bfhi(a.w); }
	v_lshlrev_b32_e32 v199, 16, v72
	v_and_b32_e32 v200, 0xffff0000, v72
	v_lshlrev_b32_e32 v201, 16, v73
	v_and_b32_e32 v202, 0xffff0000, v73
	v_lshlrev_b32_e32 v203, 16, v74
	v_and_b32_e32 v204, 0xffff0000, v74
	v_lshlrev_b32_e32 v205, 16, v75
	v_and_b32_e32 v206, 0xffff0000, v75
	v_fma_f32 v191, v150, v199, 0
	v_fma_f32 v192, v150, v200, 0
	v_fma_f32 v193, v150, v201, 0
	v_fma_f32 v194, v150, v202, 0
	v_fma_f32 v195, v150, v203, 0
	v_fma_f32 v196, v150, v204, 0
	v_fma_f32 v197, v150, v205, 0
	v_fma_f32 v198, v150, v206, 0
	v_lshlrev_b32_e32 v199, 16, v76
	v_and_b32_e32 v200, 0xffff0000, v76
	v_lshlrev_b32_e32 v201, 16, v77
	v_and_b32_e32 v202, 0xffff0000, v77
	v_lshlrev_b32_e32 v203, 16, v78
	v_and_b32_e32 v204, 0xffff0000, v78
	v_lshlrev_b32_e32 v205, 16, v79
	v_and_b32_e32 v206, 0xffff0000, v79
	v_fma_f32 v191, v151, v199, v191
	v_fma_f32 v192, v151, v200, v192
	v_fma_f32 v193, v151, v201, v193
	v_fma_f32 v194, v151, v202, v194
	v_fma_f32 v195, v151, v203, v195
	v_fma_f32 v196, v151, v204, v196
	v_fma_f32 v197, v151, v205, v197
	v_fma_f32 v198, v151, v206, v198
	v_lshlrev_b32_e32 v199, 16, v80
	v_and_b32_e32 v200, 0xffff0000, v80
	v_lshlrev_b32_e32 v201, 16, v81
	v_and_b32_e32 v202, 0xffff0000, v81
	v_lshlrev_b32_e32 v203, 16, v82
	v_and_b32_e32 v204, 0xffff0000, v82
	v_lshlrev_b32_e32 v205, 16, v83
	v_and_b32_e32 v206, 0xffff0000, v83
	v_fma_f32 v191, v152, v199, v191
	v_fma_f32 v192, v152, v200, v192
	v_fma_f32 v193, v152, v201, v193
	v_fma_f32 v194, v152, v202, v194
	v_fma_f32 v195, v152, v203, v195
	v_fma_f32 v196, v152, v204, v196
	v_fma_f32 v197, v152, v205, v197
	v_fma_f32 v198, v152, v206, v198
	v_lshlrev_b32_e32 v199, 16, v84
	v_and_b32_e32 v200, 0xffff0000, v84
	v_lshlrev_b32_e32 v201, 16, v85
	v_and_b32_e32 v202, 0xffff0000, v85
	v_lshlrev_b32_e32 v203, 16, v86
	v_and_b32_e32 v204, 0xffff0000, v86
	v_lshlrev_b32_e32 v205, 16, v87
	v_and_b32_e32 v206, 0xffff0000, v87
	v_fma_f32 v191, v153, v199, v191
	v_fma_f32 v192, v153, v200, v192
	v_fma_f32 v193, v153, v201, v193
	v_fma_f32 v194, v153, v202, v194
	v_fma_f32 v195, v153, v203, v195
	v_fma_f32 v196, v153, v204, v196
	v_fma_f32 v197, v153, v205, v197
	v_fma_f32 v198, v153, v206, v198
	v_lshlrev_b32_e32 v199, 16, v88
	v_and_b32_e32 v200, 0xffff0000, v88
	v_lshlrev_b32_e32 v201, 16, v89
	v_and_b32_e32 v202, 0xffff0000, v89
	v_lshlrev_b32_e32 v203, 16, v90
	v_and_b32_e32 v204, 0xffff0000, v90
	v_lshlrev_b32_e32 v205, 16, v91
	v_and_b32_e32 v206, 0xffff0000, v91
	v_fma_f32 v191, v154, v199, v191
	v_fma_f32 v192, v154, v200, v192
	v_fma_f32 v193, v154, v201, v193
	v_fma_f32 v194, v154, v202, v194
	v_fma_f32 v195, v154, v203, v195
	v_fma_f32 v196, v154, v204, v196
	v_fma_f32 v197, v154, v205, v197
	v_fma_f32 v198, v154, v206, v198
	v_lshlrev_b32_e32 v199, 16, v92
	v_and_b32_e32 v200, 0xffff0000, v92
	v_lshlrev_b32_e32 v201, 16, v93
	v_and_b32_e32 v202, 0xffff0000, v93
	v_lshlrev_b32_e32 v203, 16, v94
	v_and_b32_e32 v204, 0xffff0000, v94
	v_lshlrev_b32_e32 v205, 16, v95
	v_and_b32_e32 v206, 0xffff0000, v95
	v_fma_f32 v191, v155, v199, v191
	v_fma_f32 v192, v155, v200, v192
	v_fma_f32 v193, v155, v201, v193
	v_fma_f32 v194, v155, v202, v194
	v_fma_f32 v195, v155, v203, v195
	v_fma_f32 v196, v155, v204, v196
	v_fma_f32 v197, v155, v205, v197
	v_fma_f32 v198, v155, v206, v198
	v_lshlrev_b32_e32 v199, 16, v96
	v_and_b32_e32 v200, 0xffff0000, v96
	v_lshlrev_b32_e32 v201, 16, v97
	v_and_b32_e32 v202, 0xffff0000, v97
	v_lshlrev_b32_e32 v203, 16, v98
	v_and_b32_e32 v204, 0xffff0000, v98
	v_lshlrev_b32_e32 v205, 16, v99
	v_and_b32_e32 v206, 0xffff0000, v99
	v_fma_f32 v191, v156, v199, v191
	v_fma_f32 v192, v156, v200, v192
	v_fma_f32 v193, v156, v201, v193
	v_fma_f32 v194, v156, v202, v194
	v_fma_f32 v195, v156, v203, v195
	v_fma_f32 v196, v156, v204, v196
	v_fma_f32 v197, v156, v205, v197
	v_fma_f32 v198, v156, v206, v198
	v_lshlrev_b32_e32 v199, 16, v100
	v_and_b32_e32 v200, 0xffff0000, v100
	v_lshlrev_b32_e32 v201, 16, v101
	v_and_b32_e32 v202, 0xffff0000, v101
	v_lshlrev_b32_e32 v203, 16, v102
	v_and_b32_e32 v204, 0xffff0000, v102
	v_lshlrev_b32_e32 v205, 16, v103
	v_and_b32_e32 v206, 0xffff0000, v103
	v_fma_f32 v191, v157, v199, v191
	v_fma_f32 v192, v157, v200, v192
	v_fma_f32 v193, v157, v201, v193
	v_fma_f32 v194, v157, v202, v194
	v_fma_f32 v195, v157, v203, v195
	v_fma_f32 v196, v157, v204, v196
	v_fma_f32 v197, v157, v205, v197
	v_fma_f32 v198, v157, v206, v198
	v_lshlrev_b32_e32 v199, 16, v104
	v_and_b32_e32 v200, 0xffff0000, v104
	v_lshlrev_b32_e32 v201, 16, v105
	v_and_b32_e32 v202, 0xffff0000, v105
	v_lshlrev_b32_e32 v203, 16, v106
	v_and_b32_e32 v204, 0xffff0000, v106
	v_lshlrev_b32_e32 v205, 16, v107
	v_and_b32_e32 v206, 0xffff0000, v107
	v_fma_f32 v191, v158, v199, v191
	v_fma_f32 v192, v158, v200, v192
	v_fma_f32 v193, v158, v201, v193
	v_fma_f32 v194, v158, v202, v194
	v_fma_f32 v195, v158, v203, v195
	v_fma_f32 v196, v158, v204, v196
	v_fma_f32 v197, v158, v205, v197
	v_fma_f32 v198, v158, v206, v198
	v_lshlrev_b32_e32 v199, 16, v108
	v_and_b32_e32 v200, 0xffff0000, v108
	v_lshlrev_b32_e32 v201, 16, v109
	v_and_b32_e32 v202, 0xffff0000, v109
	v_lshlrev_b32_e32 v203, 16, v110
	v_and_b32_e32 v204, 0xffff0000, v110
	v_lshlrev_b32_e32 v205, 16, v111
	v_and_b32_e32 v206, 0xffff0000, v111
	v_fma_f32 v191, v159, v199, v191
	v_fma_f32 v192, v159, v200, v192
	v_fma_f32 v193, v159, v201, v193
	v_fma_f32 v194, v159, v202, v194
	v_fma_f32 v195, v159, v203, v195
	v_fma_f32 v196, v159, v204, v196
	v_fma_f32 v197, v159, v205, v197
	v_fma_f32 v198, v159, v206, v198
	v_lshlrev_b32_e32 v199, 16, v112
	v_and_b32_e32 v200, 0xffff0000, v112
	v_lshlrev_b32_e32 v201, 16, v113
; __device__ __forceinline__ unsigned cvtpk(float lo, float hi) { f32x2 v = {lo, hi}; bf16x2_t b = __builtin_convertvector(v, bf16x2_t); return __builtin_bit_cast(unsigned, b); }
; __device__ __forceinline__ float bflo(unsigned u) { return __uint_as_float(u << 16); }
; __device__ __forceinline__ float bfhi(unsigned u) { return __uint_as_float(u & 0xffff0000u); }
; template <int l> __device__ __forceinline__ void layer_body(LAS unsigned char* lds, const int wave_s) {
;     ...
;             for (int k = 0; k < 16; ++k) { const float vm = (lo + k < hi) ? 1.f : 0.f; const v4u a = av[k];
;                 s[0] += vm * bflo(a.x); s[1] += vm * bfhi(a.x); s[2] += vm * bflo(a.y); s[3] += vm * bfhi(a.y); s[4] += vm * bflo(a.z); s[5] += vm * bfhi(a.z); s[6] += vm * bflo(a.w); s[7] += vm * bfhi(a.w); }
;             const v4u me = *(const v4u*)(base + (size_t)pos * 512); const float inv = 1.0f / (float)(hi - lo);
;             v4u w; w.x = cvtpk(s[0] * inv - bflo(me.x), s[1] * inv - bfhi(me.x)); w.y = cvtpk(s[2] * inv - bflo(me.y), s[3] * inv - bfhi(me.y));
;             w.z = cvtpk(s[4] * inv - bflo(me.z), s[5] * inv - bfhi(me.z)); w.w = cvtpk(s[6] * inv - bflo(me.w), s[7] * inv - bfhi(me.w));
;             *(v4u*)(POOLEDb + (size_t)row * 512 + 8 * lane) = w;
	v_and_b32_e32 v202, 0xffff0000, v113
	v_lshlrev_b32_e32 v203, 16, v114
	v_and_b32_e32 v204, 0xffff0000, v114
	v_lshlrev_b32_e32 v205, 16, v115
	v_and_b32_e32 v206, 0xffff0000, v115
	v_fma_f32 v191, v160, v199, v191
	v_fma_f32 v192, v160, v200, v192
	v_fma_f32 v193, v160, v201, v193
	v_fma_f32 v194, v160, v202, v194
	v_fma_f32 v195, v160, v203, v195
	v_fma_f32 v196, v160, v204, v196
	v_fma_f32 v197, v160, v205, v197
	v_fma_f32 v198, v160, v206, v198
	v_lshlrev_b32_e32 v199, 16, v116
	v_and_b32_e32 v200, 0xffff0000, v116
	v_lshlrev_b32_e32 v201, 16, v117
	v_and_b32_e32 v202, 0xffff0000, v117
	v_lshlrev_b32_e32 v203, 16, v118
	v_and_b32_e32 v204, 0xffff0000, v118
	v_lshlrev_b32_e32 v205, 16, v119
	v_and_b32_e32 v206, 0xffff0000, v119
	v_fma_f32 v191, v161, v199, v191
	v_fma_f32 v192, v161, v200, v192
	v_fma_f32 v193, v161, v201, v193
	v_fma_f32 v194, v161, v202, v194
	v_fma_f32 v195, v161, v203, v195
	v_fma_f32 v196, v161, v204, v196
	v_fma_f32 v197, v161, v205, v197
	v_fma_f32 v198, v161, v206, v198
	v_lshlrev_b32_e32 v199, 16, v120
	v_and_b32_e32 v200, 0xffff0000, v120
	v_lshlrev_b32_e32 v201, 16, v121
	v_and_b32_e32 v202, 0xffff0000, v121
	v_lshlrev_b32_e32 v203, 16, v122
	v_and_b32_e32 v204, 0xffff0000, v122
	v_lshlrev_b32_e32 v205, 16, v123
	v_and_b32_e32 v206, 0xffff0000, v123
	v_fma_f32 v191, v162, v199, v191
	v_fma_f32 v192, v162, v200, v192
	v_fma_f32 v193, v162, v201, v193
	v_fma_f32 v194, v162, v202, v194
	v_fma_f32 v195, v162, v203, v195
	v_fma_f32 v196, v162, v204, v196
	v_fma_f32 v197, v162, v205, v197
	v_fma_f32 v198, v162, v206, v198
	v_lshlrev_b32_e32 v199, 16, v124
	v_and_b32_e32 v200, 0xffff0000, v124
	v_lshlrev_b32_e32 v201, 16, v125
	v_and_b32_e32 v202, 0xffff0000, v125
	v_lshlrev_b32_e32 v203, 16, v126
	v_and_b32_e32 v204, 0xffff0000, v126
	v_lshlrev_b32_e32 v205, 16, v127
	v_and_b32_e32 v206, 0xffff0000, v127
	v_fma_f32 v191, v163, v199, v191
	v_fma_f32 v192, v163, v200, v192
	v_fma_f32 v193, v163, v201, v193
	v_fma_f32 v194, v163, v202, v194
	v_fma_f32 v195, v163, v203, v195
	v_fma_f32 v196, v163, v204, v196
	v_fma_f32 v197, v163, v205, v197
	v_fma_f32 v198, v163, v206, v198
	v_lshlrev_b32_e32 v199, 16, v128
	v_and_b32_e32 v200, 0xffff0000, v128
	v_lshlrev_b32_e32 v201, 16, v129
	v_and_b32_e32 v202, 0xffff0000, v129
	v_lshlrev_b32_e32 v203, 16, v130
	v_and_b32_e32 v204, 0xffff0000, v130
	v_lshlrev_b32_e32 v205, 16, v131
	v_and_b32_e32 v206, 0xffff0000, v131
	v_fma_f32 v191, v164, v199, v191
	v_fma_f32 v192, v164, v200, v192
	v_fma_f32 v193, v164, v201, v193
	v_fma_f32 v194, v164, v202, v194
	v_fma_f32 v195, v164, v203, v195
	v_fma_f32 v196, v164, v204, v196
	v_fma_f32 v197, v164, v205, v197
	v_fma_f32 v198, v164, v206, v198
	v_lshlrev_b32_e32 v199, 16, v132
	v_and_b32_e32 v200, 0xffff0000, v132
	v_lshlrev_b32_e32 v201, 16, v133
	v_and_b32_e32 v202, 0xffff0000, v133
	v_lshlrev_b32_e32 v203, 16, v134
	v_and_b32_e32 v204, 0xffff0000, v134
	v_lshlrev_b32_e32 v205, 16, v135
	v_and_b32_e32 v206, 0xffff0000, v135
	v_fma_f32 v191, v165, v199, v191
	v_fma_f32 v192, v165, v200, v192
	v_fma_f32 v193, v165, v201, v193
	v_fma_f32 v194, v165, v202, v194
	v_fma_f32 v195, v165, v203, v195
	v_fma_f32 v196, v165, v204, v196
	v_fma_f32 v197, v165, v205, v197
	v_fma_f32 v198, v165, v206, v198
	v_lshlrev_b32_e32 v199, 16, v68
	v_and_b32_e32 v200, 0xffff0000, v68
	v_lshlrev_b32_e32 v201, 16, v69
	v_and_b32_e32 v202, 0xffff0000, v69
	v_lshlrev_b32_e32 v203, 16, v70
	v_and_b32_e32 v204, 0xffff0000, v70
	v_lshlrev_b32_e32 v205, 16, v71
	v_and_b32_e32 v206, 0xffff0000, v71
	v_fma_f32 v191, v169, v191, -v199
	v_fma_f32 v192, v169, v192, -v200
	v_fma_f32 v193, v169, v193, -v201
	v_fma_f32 v194, v169, v194, -v202
	v_fma_f32 v195, v169, v195, -v203
	v_fma_f32 v196, v169, v196, -v204
	v_fma_f32 v197, v169, v197, -v205
	v_fma_f32 v198, v169, v198, -v206
	v_cvt_pk_bf16_f32 v208, v191, v192
	v_cvt_pk_bf16_f32 v209, v193, v194
	v_cvt_pk_bf16_f32 v210, v195, v196
	v_cvt_pk_bf16_f32 v211, v197, v198
	global_store_dwordx4 v175, v[208:211], s[24:25] offset:768
	v_subrev_u32_e32 v176, 8, v172
	v_add_u32_e32 v177, 8, v172
	v_max_i32_e32 v176, 0, v176
	v_min_i32_e32 v177, s19, v177
	v_lshl_add_u32 v187, v172, 10, v173
	v_sub_u32_e32 v178, v177, v176
	global_load_dwordx4 v[68:71], v187, s[22:23] offset:768
	v_lshl_add_u32 v188, v176, 10, v173
	v_mov_b32_e32 v150, 1.0
; template <int l> __device__ __forceinline__ void layer_body(LAS unsigned char* lds, const int wave_s) {
;     ...
;         for (int row = gw; row < rows_post; row += NGW) {
;             int pos, Ls; if (row < TL) { pos = row & 63; Ls = 64; } else { pos = (row - TL) & 255; Ls = 256; }
;             const int hw = 1 << (lane >> 4);
;             const int lo = max(pos - hw, 0), hi = min(pos + hw, Ls);
;             const bf16* base = POOLb + (size_t)(row - pos) * 512 + 8 * lane;
;             float s[8];
; #pragma unroll
;             for (int e = 0; e < 8; ++e) s[e] = 0.f;
;             v4u av[16];
; #pragma unroll
;             for (int k = 0; k < 16; ++k) { const int p = lo + k; const int pc = p < hi ? p : pos; av[k] = *(const v4u*)(base + (size_t)pc * 512); }
	global_load_dwordx4 v[72:75], v188, s[22:23] offset:768
	v_add_u32_e32 v179, 1, v176
	v_add_u32_e32 v180, 2, v176
	v_add_u32_e32 v181, 3, v176
	v_add_u32_e32 v182, 4, v176
	v_cmp_lt_i32_e64 s[30:31], v179, v177
	v_cmp_lt_i32_e64 s[34:35], v180, v177
	v_cmp_lt_i32_e64 s[36:37], v181, v177
	v_cmp_lt_i32_e64 s[38:39], v182, v177
	v_cndmask_b32_e64 v183, v172, v179, s[30:31]
	v_cndmask_b32_e64 v151, 0, 1.0, s[30:31]
	v_lshl_add_u32 v187, v183, 10, v173
	global_load_dwordx4 v[76:79], v187, s[22:23] offset:768
	v_cndmask_b32_e64 v184, v172, v180, s[34:35]
	v_cndmask_b32_e64 v152, 0, 1.0, s[34:35]
	v_lshl_add_u32 v188, v184, 10, v173
	global_load_dwordx4 v[80:83], v188, s[22:23] offset:768
	v_cndmask_b32_e64 v185, v172, v181, s[36:37]
	v_cndmask_b32_e64 v153, 0, 1.0, s[36:37]
	v_lshl_add_u32 v189, v185, 10, v173
	global_load_dwordx4 v[84:87], v189, s[22:23] offset:768
	v_cndmask_b32_e64 v186, v172, v182, s[38:39]
	v_cndmask_b32_e64 v154, 0, 1.0, s[38:39]
	v_lshl_add_u32 v190, v186, 10, v173
	global_load_dwordx4 v[88:91], v190, s[22:23] offset:768
	v_add_u32_e32 v179, 5, v176
	v_add_u32_e32 v180, 6, v176
	v_add_u32_e32 v181, 7, v176
	v_add_u32_e32 v182, 8, v176
	v_cmp_lt_i32_e64 s[30:31], v179, v177
	v_cmp_lt_i32_e64 s[34:35], v180, v177
	v_cmp_lt_i32_e64 s[36:37], v181, v177
	v_cmp_lt_i32_e64 s[38:39], v182, v177
	v_cndmask_b32_e64 v183, v172, v179, s[30:31]
	v_cndmask_b32_e64 v155, 0, 1.0, s[30:31]
	v_lshl_add_u32 v187, v183, 10, v173
	global_load_dwordx4 v[92:95], v187, s[22:23] offset:768
	v_cndmask_b32_e64 v184, v172, v180, s[34:35]
	v_cndmask_b32_e64 v156, 0, 1.0, s[34:35]
	v_lshl_add_u32 v188, v184, 10, v173
	global_load_dwordx4 v[96:99], v188, s[22:23] offset:768
	v_cndmask_b32_e64 v185, v172, v181, s[36:37]
	v_cndmask_b32_e64 v157, 0, 1.0, s[36:37]
	v_lshl_add_u32 v189, v185, 10, v173
	global_load_dwordx4 v[100:103], v189, s[22:23] offset:768
	v_cndmask_b32_e64 v186, v172, v182, s[38:39]
	v_cndmask_b32_e64 v158, 0, 1.0, s[38:39]
	v_lshl_add_u32 v190, v186, 10, v173
	global_load_dwordx4 v[104:107], v190, s[22:23] offset:768
	v_add_u32_e32 v179, 9, v176
	v_add_u32_e32 v180, 10, v176
	v_add_u32_e32 v181, 11, v176
	v_add_u32_e32 v182, 12, v176
	v_cmp_lt_i32_e64 s[30:31], v179, v177
	v_cmp_lt_i32_e64 s[34:35], v180, v177
	v_cmp_lt_i32_e64 s[36:37], v181, v177
	v_cmp_lt_i32_e64 s[38:39], v182, v177
	v_cndmask_b32_e64 v183, v172, v179, s[30:31]
	v_cndmask_b32_e64 v159, 0, 1.0, s[30:31]
	v_lshl_add_u32 v187, v183, 10, v173
	global_load_dwordx4 v[108:111], v187, s[22:23] offset:768
	v_cndmask_b32_e64 v184, v172, v180, s[34:35]
	v_cndmask_b32_e64 v160, 0, 1.0, s[34:35]
	v_lshl_add_u32 v188, v184, 10, v173
	global_load_dwordx4 v[112:115], v188, s[22:23] offset:768
	v_cndmask_b32_e64 v185, v172, v181, s[36:37]
	v_cndmask_b32_e64 v161, 0, 1.0, s[36:37]
	v_lshl_add_u32 v189, v185, 10, v173
	global_load_dwordx4 v[116:119], v189, s[22:23] offset:768
	v_cndmask_b32_e64 v186, v172, v182, s[38:39]
	v_cndmask_b32_e64 v162, 0, 1.0, s[38:39]
	v_lshl_add_u32 v190, v186, 10, v173
	global_load_dwordx4 v[120:123], v190, s[22:23] offset:768
	v_add_u32_e32 v179, 13, v176
	v_add_u32_e32 v180, 14, v176
	v_add_u32_e32 v181, 15, v176
	v_cmp_lt_i32_e64 s[30:31], v179, v177
	v_cmp_lt_i32_e64 s[34:35], v180, v177
	v_cmp_lt_i32_e64 s[36:37], v181, v177
	v_cndmask_b32_e64 v183, v172, v179, s[30:31]
	v_cndmask_b32_e64 v163, 0, 1.0, s[30:31]
	v_lshl_add_u32 v187, v183, 10, v173
	global_load_dwordx4 v[124:127], v187, s[22:23] offset:768
	v_cndmask_b32_e64 v184, v172, v180, s[34:35]
	v_cndmask_b32_e64 v164, 0, 1.0, s[34:35]
	v_lshl_add_u32 v188, v184, 10, v173
	global_load_dwordx4 v[128:131], v188, s[22:23] offset:768
	v_cndmask_b32_e64 v185, v172, v181, s[36:37]
	v_cndmask_b32_e64 v165, 0, 1.0, s[36:37]
	v_lshl_add_u32 v189, v185, 10, v173
	global_load_dwordx4 v[132:135], v189, s[22:23] offset:768
	v_cvt_f32_i32_e32 v178, v178
	v_div_scale_f32 v212, s[40:41], v178, v178, 1.0
	v_div_scale_f32 v215, vcc, 1.0, v178, 1.0
	v_rcp_f32_e32 v213, v212
	s_nop 0
	v_fma_f32 v214, -v212, v213, 1.0
	v_fmac_f32_e32 v213, v214, v213
	v_mul_f32_e32 v216, v215, v213
	v_fma_f32 v217, -v212, v216, v215
	v_fmac_f32_e32 v216, v217, v213
	v_fma_f32 v218, -v212, v216, v215
	v_div_fmas_f32 v219, v218, v213, v216
	v_div_fixup_f32 v169, v219, v178, 1.0
	s_cmp_eq_u32 s29, 1
	s_cbranch_scc1 .Lc1_loop_L3
